# K-loop turnaround trim: s_setprio 1 before the burst-opening barrier, redundant post-barrier lgkmcnt(0) dropped (first instruction after release is the first MFMA), 5 K-loops
# speedup vs baseline: 1.0089x; 1.0089x over previous
.LBB0_207:
	ds_read_b128 v[156:159], v152
	ds_read_b128 v[160:163], v152 offset:1024
	ds_read_b128 v[164:167], v152 offset:2048
	ds_read_b128 v[168:171], v152 offset:3072
	ds_read_b128 v[172:175], v153
	ds_read_b128 v[176:179], v153 offset:1024
	ds_read_b128 v[180:183], v153 offset:2048
	ds_read_b128 v[184:187], v153 offset:3072
	s_add_u32 s36, s0, 0xfffe0080
	s_addc_u32 s37, s1, -1
	s_cmp_eq_u32 s62, 4
	s_cselect_b32 s39, s25, s37
	s_cselect_b32 s38, s27, s36
	s_cselect_b32 s37, s29, s61
	s_cselect_b32 s36, s28, s60
	v_lshl_add_u64 v[146:147], s[0:1], 0, v[138:139]
	s_add_i32 m0, s35, 0xc000
	ds_read_b128 v[188:191], v154
	ds_read_b128 v[192:195], v154 offset:1024
	ds_read_b128 v[196:199], v154 offset:2048
	ds_read_b128 v[200:203], v154 offset:3072
	ds_read_b128 v[204:207], v154 offset:4096
	ds_read_b128 v[208:211], v154 offset:5120
	ds_read_b128 v[212:215], v154 offset:6144
	ds_read_b128 v[216:219], v154 offset:7168
	global_load_lds_dwordx4 v[146:147], off
	v_lshl_add_u64 v[146:147], s[0:1], 0, v[140:141]
	s_add_i32 m0, s35, 0xe000
	s_nop 0
	global_load_lds_dwordx4 v[146:147], off
	s_waitcnt vmcnt(8)
	s_waitcnt lgkmcnt(0)
	s_setprio 1
	s_barrier
	v_mfma_f32_16x16x32_bf16 v[126:129], v[156:159], v[188:191], v[126:129]
	v_mfma_f32_16x16x32_bf16 v[122:125], v[164:167], v[188:191], v[122:125]
	v_mfma_f32_16x16x32_bf16 v[118:121], v[156:159], v[196:199], v[118:121]
	v_mfma_f32_16x16x32_bf16 v[110:113], v[164:167], v[196:199], v[110:113]
	v_mfma_f32_16x16x32_bf16 v[102:105], v[156:159], v[204:207], v[102:105]
	v_mfma_f32_16x16x32_bf16 v[94:97], v[164:167], v[204:207], v[94:97]
	v_mfma_f32_16x16x32_bf16 v[86:89], v[156:159], v[212:215], v[86:89]
	v_mfma_f32_16x16x32_bf16 v[78:81], v[164:167], v[212:215], v[78:81]
	v_mfma_f32_16x16x32_bf16 v[126:129], v[160:163], v[192:195], v[126:129]
	v_mfma_f32_16x16x32_bf16 v[122:125], v[168:171], v[192:195], v[122:125]
	v_mfma_f32_16x16x32_bf16 v[118:121], v[160:163], v[200:203], v[118:121]
	v_mfma_f32_16x16x32_bf16 v[110:113], v[168:171], v[200:203], v[110:113]
	v_mfma_f32_16x16x32_bf16 v[102:105], v[160:163], v[208:211], v[102:105]
	v_mfma_f32_16x16x32_bf16 v[94:97], v[168:171], v[208:211], v[94:97]
	v_mfma_f32_16x16x32_bf16 v[86:89], v[160:163], v[216:219], v[86:89]
	v_mfma_f32_16x16x32_bf16 v[78:81], v[168:171], v[216:219], v[78:81]
	s_setprio 0
	s_setprio 1
	v_mfma_f32_16x16x32_bf16 v[114:117], v[172:175], v[188:191], v[114:117]
	v_mfma_f32_16x16x32_bf16 v[106:109], v[180:183], v[188:191], v[106:109]
	v_mfma_f32_16x16x32_bf16 v[98:101], v[172:175], v[196:199], v[98:101]
	v_mfma_f32_16x16x32_bf16 v[90:93], v[180:183], v[196:199], v[90:93]
	v_mfma_f32_16x16x32_bf16 v[82:85], v[172:175], v[204:207], v[82:85]
	v_mfma_f32_16x16x32_bf16 v[74:77], v[180:183], v[204:207], v[74:77]
	v_mfma_f32_16x16x32_bf16 v[70:73], v[172:175], v[212:215], v[70:73]
	v_mfma_f32_16x16x32_bf16 v[66:69], v[180:183], v[212:215], v[66:69]
	v_mfma_f32_16x16x32_bf16 v[114:117], v[176:179], v[192:195], v[114:117]
	v_mfma_f32_16x16x32_bf16 v[106:109], v[184:187], v[192:195], v[106:109]
	v_mfma_f32_16x16x32_bf16 v[98:101], v[176:179], v[200:203], v[98:101]
	v_mfma_f32_16x16x32_bf16 v[90:93], v[184:187], v[200:203], v[90:93]
	v_mfma_f32_16x16x32_bf16 v[82:85], v[176:179], v[208:211], v[82:85]
	v_mfma_f32_16x16x32_bf16 v[74:77], v[184:187], v[208:211], v[74:77]
	v_mfma_f32_16x16x32_bf16 v[70:73], v[176:179], v[216:219], v[70:73]
	v_mfma_f32_16x16x32_bf16 v[66:69], v[184:187], v[216:219], v[66:69]
	s_setprio 0
	s_barrier
	s_add_i32 s63, s53, s43
	v_lshl_add_u64 v[146:147], s[36:37], 0, v[132:133]
	s_mov_b32 m0, s63
	ds_read_b128 v[188:191], v154 offset:16384
	ds_read_b128 v[192:195], v154 offset:17408
	ds_read_b128 v[196:199], v154 offset:18432
	ds_read_b128 v[200:203], v154 offset:19456
	ds_read_b128 v[204:207], v154 offset:20480
	ds_read_b128 v[208:211], v154 offset:21504
	ds_read_b128 v[212:215], v154 offset:22528
	ds_read_b128 v[216:219], v154 offset:23552
	global_load_lds_dwordx4 v[146:147], off
	s_add_i32 m0, s63, 0x2000
	s_add_u32 s64, s36, 0x80000
	v_lshl_add_u64 v[220:221], s[36:37], 0, v[136:137]
	s_addc_u32 s65, s37, 0
	s_add_i32 s63, s54, s43
	global_load_lds_dwordx4 v[220:221], off
	v_lshl_add_u64 v[222:223], s[64:65], 0, v[132:133]
	s_mov_b32 m0, s63
	v_lshl_add_u64 v[224:225], s[38:39], 0, v[134:135]
	global_load_lds_dwordx4 v[222:223], off
	v_lshl_add_u64 v[222:223], s[64:65], 0, v[136:137]
	s_add_i32 m0, s63, 0x2000
	s_nop 0
	global_load_lds_dwordx4 v[222:223], off
	v_lshl_add_u64 v[222:223], s[38:39], 0, v[130:131]
	s_mov_b32 m0, s35
	s_nop 0
	global_load_lds_dwordx4 v[222:223], off
	s_mov_b32 m0, s46
	s_nop 0
	global_load_lds_dwordx4 v[224:225], off
	s_waitcnt vmcnt(8)
	s_waitcnt lgkmcnt(0)
	s_setprio 1
	s_barrier
	v_mfma_f32_16x16x32_bf16 v[62:65], v[156:159], v[188:191], v[62:65]
	v_mfma_f32_16x16x32_bf16 v[58:61], v[164:167], v[188:191], v[58:61]
	v_mfma_f32_16x16x32_bf16 v[54:57], v[156:159], v[196:199], v[54:57]
	v_mfma_f32_16x16x32_bf16 v[46:49], v[164:167], v[196:199], v[46:49]
	v_mfma_f32_16x16x32_bf16 v[38:41], v[156:159], v[204:207], v[38:41]
	v_mfma_f32_16x16x32_bf16 v[30:33], v[164:167], v[204:207], v[30:33]
	v_mfma_f32_16x16x32_bf16 v[22:25], v[156:159], v[212:215], v[22:25]
	v_mfma_f32_16x16x32_bf16 v[14:17], v[164:167], v[212:215], v[14:17]
	v_mfma_f32_16x16x32_bf16 v[62:65], v[160:163], v[192:195], v[62:65]
	v_mfma_f32_16x16x32_bf16 v[58:61], v[168:171], v[192:195], v[58:61]
	v_mfma_f32_16x16x32_bf16 v[54:57], v[160:163], v[200:203], v[54:57]
	v_mfma_f32_16x16x32_bf16 v[46:49], v[168:171], v[200:203], v[46:49]
	v_mfma_f32_16x16x32_bf16 v[38:41], v[160:163], v[208:211], v[38:41]
	v_mfma_f32_16x16x32_bf16 v[30:33], v[168:171], v[208:211], v[30:33]
	v_mfma_f32_16x16x32_bf16 v[22:25], v[160:163], v[216:219], v[22:25]
	v_mfma_f32_16x16x32_bf16 v[14:17], v[168:171], v[216:219], v[14:17]
	s_setprio 0
	s_setprio 1
	v_mfma_f32_16x16x32_bf16 v[50:53], v[172:175], v[188:191], v[50:53]
	v_mfma_f32_16x16x32_bf16 v[42:45], v[180:183], v[188:191], v[42:45]
	v_mfma_f32_16x16x32_bf16 v[34:37], v[172:175], v[196:199], v[34:37]
	v_mfma_f32_16x16x32_bf16 v[26:29], v[180:183], v[196:199], v[26:29]
	v_mfma_f32_16x16x32_bf16 v[18:21], v[172:175], v[204:207], v[18:21]
	v_mfma_f32_16x16x32_bf16 v[10:13], v[180:183], v[204:207], v[10:13]
	v_mfma_f32_16x16x32_bf16 v[6:9], v[172:175], v[212:215], v[6:9]
	v_mfma_f32_16x16x32_bf16 v[2:5], v[180:183], v[212:215], v[2:5]
	v_mfma_f32_16x16x32_bf16 v[50:53], v[176:179], v[192:195], v[50:53]
	v_mfma_f32_16x16x32_bf16 v[42:45], v[184:187], v[192:195], v[42:45]
	v_mfma_f32_16x16x32_bf16 v[34:37], v[176:179], v[200:203], v[34:37]
	v_mfma_f32_16x16x32_bf16 v[26:29], v[184:187], v[200:203], v[26:29]
	v_mfma_f32_16x16x32_bf16 v[18:21], v[176:179], v[208:211], v[18:21]
	v_mfma_f32_16x16x32_bf16 v[10:13], v[184:187], v[208:211], v[10:13]
	v_mfma_f32_16x16x32_bf16 v[6:9], v[176:179], v[216:219], v[6:9]
	v_mfma_f32_16x16x32_bf16 v[2:5], v[184:187], v[216:219], v[2:5]
	s_setprio 0
	s_barrier
	s_add_i32 s63, 0, 0x18000
	v_add_u32_e32 v155, s63, v150
	s_add_i32 s64, 0, 0x1c000
	ds_read_b128 v[156:159], v155
	ds_read_b128 v[160:163], v155 offset:1024
	ds_read_b128 v[164:167], v155 offset:2048
	ds_read_b128 v[168:171], v155 offset:3072
	v_add_u32_e32 v155, s64, v150
	ds_read_b128 v[172:175], v155
	ds_read_b128 v[176:179], v155 offset:1024
	ds_read_b128 v[180:183], v155 offset:2048
	ds_read_b128 v[184:187], v155 offset:3072
	s_add_u32 s38, s38, 0x20000
	s_addc_u32 s39, s39, 0
	s_mov_b32 m0, s47
	v_lshl_add_u64 v[226:227], s[38:39], 0, v[130:131]
	ds_read_b128 v[188:191], v154 offset:32768
	ds_read_b128 v[192:195], v154 offset:33792
	ds_read_b128 v[196:199], v154 offset:34816
	ds_read_b128 v[200:203], v154 offset:35840
	ds_read_b128 v[204:207], v154 offset:36864
	ds_read_b128 v[208:211], v154 offset:37888
	ds_read_b128 v[212:215], v154 offset:38912
	ds_read_b128 v[216:219], v154 offset:39936
	global_load_lds_dwordx4 v[226:227], off
	v_lshl_add_u64 v[226:227], s[38:39], 0, v[134:135]
	s_mov_b32 m0, s48
	s_nop 0
	global_load_lds_dwordx4 v[226:227], off
	s_waitcnt vmcnt(8)
	s_waitcnt lgkmcnt(0)
	s_setprio 1
	s_barrier
	v_mfma_f32_16x16x32_bf16 v[126:129], v[156:159], v[188:191], v[126:129]
	v_mfma_f32_16x16x32_bf16 v[122:125], v[164:167], v[188:191], v[122:125]
	v_mfma_f32_16x16x32_bf16 v[118:121], v[156:159], v[196:199], v[118:121]
	v_mfma_f32_16x16x32_bf16 v[110:113], v[164:167], v[196:199], v[110:113]
	v_mfma_f32_16x16x32_bf16 v[102:105], v[156:159], v[204:207], v[102:105]
	v_mfma_f32_16x16x32_bf16 v[94:97], v[164:167], v[204:207], v[94:97]
	v_mfma_f32_16x16x32_bf16 v[86:89], v[156:159], v[212:215], v[86:89]
	v_mfma_f32_16x16x32_bf16 v[78:81], v[164:167], v[212:215], v[78:81]
	v_mfma_f32_16x16x32_bf16 v[126:129], v[160:163], v[192:195], v[126:129]
	v_mfma_f32_16x16x32_bf16 v[122:125], v[168:171], v[192:195], v[122:125]
	v_mfma_f32_16x16x32_bf16 v[118:121], v[160:163], v[200:203], v[118:121]
	v_mfma_f32_16x16x32_bf16 v[110:113], v[168:171], v[200:203], v[110:113]
	v_mfma_f32_16x16x32_bf16 v[102:105], v[160:163], v[208:211], v[102:105]
	v_mfma_f32_16x16x32_bf16 v[94:97], v[168:171], v[208:211], v[94:97]
	v_mfma_f32_16x16x32_bf16 v[86:89], v[160:163], v[216:219], v[86:89]
	v_mfma_f32_16x16x32_bf16 v[78:81], v[168:171], v[216:219], v[78:81]
	s_setprio 0
	s_setprio 1
	v_mfma_f32_16x16x32_bf16 v[114:117], v[172:175], v[188:191], v[114:117]
	v_mfma_f32_16x16x32_bf16 v[106:109], v[180:183], v[188:191], v[106:109]
	v_mfma_f32_16x16x32_bf16 v[98:101], v[172:175], v[196:199], v[98:101]
	v_mfma_f32_16x16x32_bf16 v[90:93], v[180:183], v[196:199], v[90:93]
	v_mfma_f32_16x16x32_bf16 v[82:85], v[172:175], v[204:207], v[82:85]
	v_mfma_f32_16x16x32_bf16 v[74:77], v[180:183], v[204:207], v[74:77]
	v_mfma_f32_16x16x32_bf16 v[70:73], v[172:175], v[212:215], v[70:73]
	v_mfma_f32_16x16x32_bf16 v[66:69], v[180:183], v[212:215], v[66:69]
	v_mfma_f32_16x16x32_bf16 v[114:117], v[176:179], v[192:195], v[114:117]
	v_mfma_f32_16x16x32_bf16 v[106:109], v[184:187], v[192:195], v[106:109]
	v_mfma_f32_16x16x32_bf16 v[98:101], v[176:179], v[200:203], v[98:101]
	v_mfma_f32_16x16x32_bf16 v[90:93], v[184:187], v[200:203], v[90:93]
	v_mfma_f32_16x16x32_bf16 v[82:85], v[176:179], v[208:211], v[82:85]
	v_mfma_f32_16x16x32_bf16 v[74:77], v[184:187], v[208:211], v[74:77]
	v_mfma_f32_16x16x32_bf16 v[70:73], v[176:179], v[216:219], v[70:73]
	v_mfma_f32_16x16x32_bf16 v[66:69], v[184:187], v[216:219], v[66:69]
	s_setprio 0
	s_barrier
	s_add_i32 s38, s63, s43
	v_lshl_add_u64 v[146:147], v[146:147], 0, s[8:9]
	s_mov_b32 m0, s38
	ds_read_b128 v[188:191], v154 offset:49152
	ds_read_b128 v[192:195], v154 offset:50176
	ds_read_b128 v[196:199], v154 offset:51200
	ds_read_b128 v[200:203], v154 offset:52224
	ds_read_b128 v[204:207], v154 offset:53248
	ds_read_b128 v[208:211], v154 offset:54272
	ds_read_b128 v[212:215], v154 offset:55296
	ds_read_b128 v[216:219], v154 offset:56320
	global_load_lds_dwordx4 v[146:147], off
	s_add_i32 m0, s38, 0x2000
	s_add_u32 s36, s36, 0x80080
	v_lshl_add_u64 v[146:147], v[220:221], 0, s[8:9]
	s_addc_u32 s37, s37, 0
	s_add_i32 s38, s64, s43
	global_load_lds_dwordx4 v[146:147], off
	v_lshl_add_u64 v[146:147], s[36:37], 0, v[132:133]
	s_mov_b32 m0, s38
	s_nop 0
	global_load_lds_dwordx4 v[146:147], off
	v_lshl_add_u64 v[146:147], s[36:37], 0, v[136:137]
	s_add_i32 m0, s38, 0x2000
	s_nop 0
	global_load_lds_dwordx4 v[146:147], off
	v_lshl_add_u64 v[146:147], v[222:223], 0, s[8:9]
	s_mov_b32 m0, s50
	s_nop 0
	global_load_lds_dwordx4 v[146:147], off
	v_lshl_add_u64 v[146:147], v[224:225], 0, s[8:9]
	s_mov_b32 m0, s51
	s_nop 0
	global_load_lds_dwordx4 v[146:147], off
	s_waitcnt vmcnt(8)
	s_waitcnt lgkmcnt(0)
	s_setprio 1
	s_barrier
	v_mfma_f32_16x16x32_bf16 v[62:65], v[156:159], v[188:191], v[62:65]
	v_mfma_f32_16x16x32_bf16 v[58:61], v[164:167], v[188:191], v[58:61]
	v_mfma_f32_16x16x32_bf16 v[54:57], v[156:159], v[196:199], v[54:57]
	v_mfma_f32_16x16x32_bf16 v[46:49], v[164:167], v[196:199], v[46:49]
	v_mfma_f32_16x16x32_bf16 v[38:41], v[156:159], v[204:207], v[38:41]
	v_mfma_f32_16x16x32_bf16 v[30:33], v[164:167], v[204:207], v[30:33]
	v_mfma_f32_16x16x32_bf16 v[22:25], v[156:159], v[212:215], v[22:25]
	v_mfma_f32_16x16x32_bf16 v[14:17], v[164:167], v[212:215], v[14:17]
	v_mfma_f32_16x16x32_bf16 v[62:65], v[160:163], v[192:195], v[62:65]
	v_mfma_f32_16x16x32_bf16 v[58:61], v[168:171], v[192:195], v[58:61]
	v_mfma_f32_16x16x32_bf16 v[54:57], v[160:163], v[200:203], v[54:57]
	v_mfma_f32_16x16x32_bf16 v[46:49], v[168:171], v[200:203], v[46:49]
	v_mfma_f32_16x16x32_bf16 v[38:41], v[160:163], v[208:211], v[38:41]
	v_mfma_f32_16x16x32_bf16 v[30:33], v[168:171], v[208:211], v[30:33]
	v_mfma_f32_16x16x32_bf16 v[22:25], v[160:163], v[216:219], v[22:25]
	v_mfma_f32_16x16x32_bf16 v[14:17], v[168:171], v[216:219], v[14:17]
	s_setprio 0
	s_setprio 1
	v_mfma_f32_16x16x32_bf16 v[50:53], v[172:175], v[188:191], v[50:53]
	v_mfma_f32_16x16x32_bf16 v[42:45], v[180:183], v[188:191], v[42:45]
	v_mfma_f32_16x16x32_bf16 v[34:37], v[172:175], v[196:199], v[34:37]
	v_mfma_f32_16x16x32_bf16 v[26:29], v[180:183], v[196:199], v[26:29]
	v_mfma_f32_16x16x32_bf16 v[18:21], v[172:175], v[204:207], v[18:21]
	v_mfma_f32_16x16x32_bf16 v[10:13], v[180:183], v[204:207], v[10:13]
	v_mfma_f32_16x16x32_bf16 v[6:9], v[172:175], v[212:215], v[6:9]
	v_mfma_f32_16x16x32_bf16 v[2:5], v[180:183], v[212:215], v[2:5]
	v_mfma_f32_16x16x32_bf16 v[50:53], v[176:179], v[192:195], v[50:53]
	v_mfma_f32_16x16x32_bf16 v[42:45], v[184:187], v[192:195], v[42:45]
	v_mfma_f32_16x16x32_bf16 v[34:37], v[176:179], v[200:203], v[34:37]
	v_mfma_f32_16x16x32_bf16 v[26:29], v[184:187], v[200:203], v[26:29]
	v_mfma_f32_16x16x32_bf16 v[18:21], v[176:179], v[208:211], v[18:21]
	v_mfma_f32_16x16x32_bf16 v[10:13], v[184:187], v[208:211], v[10:13]
	v_mfma_f32_16x16x32_bf16 v[6:9], v[176:179], v[216:219], v[6:9]
	v_mfma_f32_16x16x32_bf16 v[2:5], v[184:187], v[216:219], v[2:5]
	s_setprio 0
	s_barrier
	s_add_i32 s62, s62, 2
	s_add_u32 s0, s0, 0x100
	s_addc_u32 s1, s1, 0
	s_add_u32 s60, s60, 0x100
	s_addc_u32 s61, s61, 0
	s_cmp_gt_u32 s62, 5
	s_cbranch_scc0 .LBB0_207
	s_and_b64 vcc, exec, s[10:11]
	s_cbranch_vccz .LBB0_210
	s_barrier

.LBB0_290:
	s_add_u32 s12, s60, s10
	s_addc_u32 s13, s61, s11
	s_add_u32 s12, s12, 0x100
	s_addc_u32 s13, s13, 0
	s_add_u32 s97, s28, s10
	s_addc_u32 vcc_lo, s29, s11
	s_add_i32 vcc_hi, 0, 0x10000
	s_cmpk_eq_i32 s10, 0xf00
	s_cselect_b32 s41, s63, s13
	s_cselect_b32 s40, s94, s12
	v_add_u32_e32 v154, vcc_hi, v169
	s_cselect_b32 s13, s67, vcc_lo
	s_cselect_b32 s12, s95, s97
	s_add_i32 s97, 0, 0x14000
	ds_read_b128 v[146:149], v154
	ds_read_b128 v[150:153], v154 offset:1024
	ds_read_b128 v[164:167], v154 offset:2048
	ds_read_b128 v[172:175], v154 offset:3072
	v_add_u32_e32 v154, s97, v169
	ds_read_b128 v[176:179], v154
	ds_read_b128 v[180:183], v154 offset:1024
	ds_read_b128 v[184:187], v154 offset:2048
	ds_read_b128 v[188:191], v154 offset:3072
	v_lshl_add_u64 v[196:197], v[142:143], 0, s[10:11]
	s_add_i32 m0, s81, 0xc000
	ds_read_b128 v[200:203], v171
	ds_read_b128 v[204:207], v171 offset:1024
	ds_read_b128 v[208:211], v171 offset:2048
	ds_read_b128 v[212:215], v171 offset:3072
	ds_read_b128 v[216:219], v171 offset:4096
	ds_read_b128 v[220:223], v171 offset:5120
	ds_read_b128 v[224:227], v171 offset:6144
	ds_read_b128 v[228:231], v171 offset:7168
	global_load_lds_dwordx4 v[196:197], off
	v_lshl_add_u64 v[196:197], v[144:145], 0, s[10:11]
	s_add_i32 m0, s81, 0xe000
	s_nop 0
	global_load_lds_dwordx4 v[196:197], off
	s_waitcnt vmcnt(8)
	s_waitcnt lgkmcnt(0)
	s_setprio 1
	s_barrier
	v_mfma_f32_16x16x32_bf16 v[126:129], v[146:149], v[200:203], v[126:129]
	v_mfma_f32_16x16x32_bf16 v[122:125], v[164:167], v[200:203], v[122:125]
	v_mfma_f32_16x16x32_bf16 v[118:121], v[146:149], v[208:211], v[118:121]
	v_mfma_f32_16x16x32_bf16 v[114:117], v[164:167], v[208:211], v[114:117]
	v_mfma_f32_16x16x32_bf16 v[110:113], v[146:149], v[216:219], v[110:113]
	v_mfma_f32_16x16x32_bf16 v[106:109], v[164:167], v[216:219], v[106:109]
	v_mfma_f32_16x16x32_bf16 v[102:105], v[146:149], v[224:227], v[102:105]
	v_mfma_f32_16x16x32_bf16 v[98:101], v[164:167], v[224:227], v[98:101]
	v_mfma_f32_16x16x32_bf16 v[126:129], v[150:153], v[204:207], v[126:129]
	v_mfma_f32_16x16x32_bf16 v[122:125], v[172:175], v[204:207], v[122:125]
	v_mfma_f32_16x16x32_bf16 v[118:121], v[150:153], v[212:215], v[118:121]
	v_mfma_f32_16x16x32_bf16 v[114:117], v[172:175], v[212:215], v[114:117]
	v_mfma_f32_16x16x32_bf16 v[110:113], v[150:153], v[220:223], v[110:113]
	v_mfma_f32_16x16x32_bf16 v[106:109], v[172:175], v[220:223], v[106:109]
	v_mfma_f32_16x16x32_bf16 v[102:105], v[150:153], v[228:231], v[102:105]
	v_mfma_f32_16x16x32_bf16 v[98:101], v[172:175], v[228:231], v[98:101]
	s_setprio 0
	s_setprio 1
	v_mfma_f32_16x16x32_bf16 v[94:97], v[176:179], v[200:203], v[94:97]
	v_mfma_f32_16x16x32_bf16 v[90:93], v[184:187], v[200:203], v[90:93]
	v_mfma_f32_16x16x32_bf16 v[86:89], v[176:179], v[208:211], v[86:89]
	v_mfma_f32_16x16x32_bf16 v[82:85], v[184:187], v[208:211], v[82:85]
	v_mfma_f32_16x16x32_bf16 v[78:81], v[176:179], v[216:219], v[78:81]
	v_mfma_f32_16x16x32_bf16 v[74:77], v[184:187], v[216:219], v[74:77]
	v_mfma_f32_16x16x32_bf16 v[70:73], v[176:179], v[224:227], v[70:73]
	v_mfma_f32_16x16x32_bf16 v[66:69], v[184:187], v[224:227], v[66:69]
	v_mfma_f32_16x16x32_bf16 v[94:97], v[180:183], v[204:207], v[94:97]
	v_mfma_f32_16x16x32_bf16 v[90:93], v[188:191], v[204:207], v[90:93]
	v_mfma_f32_16x16x32_bf16 v[86:89], v[180:183], v[212:215], v[86:89]
	v_mfma_f32_16x16x32_bf16 v[82:85], v[188:191], v[212:215], v[82:85]
	v_mfma_f32_16x16x32_bf16 v[78:81], v[180:183], v[220:223], v[78:81]
	v_mfma_f32_16x16x32_bf16 v[74:77], v[188:191], v[220:223], v[74:77]
	v_mfma_f32_16x16x32_bf16 v[70:73], v[180:183], v[228:231], v[70:73]
	v_mfma_f32_16x16x32_bf16 v[66:69], v[188:191], v[228:231], v[66:69]
	s_setprio 0
	s_barrier
	s_add_i32 vcc_lo, vcc_hi, s80
	v_lshl_add_u64 v[196:197], s[12:13], 0, v[132:133]
	s_mov_b32 m0, vcc_lo
	ds_read_b128 v[200:203], v171 offset:16384
	ds_read_b128 v[204:207], v171 offset:17408
	ds_read_b128 v[208:211], v171 offset:18432
	ds_read_b128 v[212:215], v171 offset:19456
	ds_read_b128 v[216:219], v171 offset:20480
	ds_read_b128 v[220:223], v171 offset:21504
	ds_read_b128 v[224:227], v171 offset:22528
	ds_read_b128 v[228:231], v171 offset:23552
	global_load_lds_dwordx4 v[196:197], off
	s_add_i32 m0, vcc_lo, 0x2000
	s_add_u32 vcc_lo, s12, 0x80000
	v_lshl_add_u64 v[232:233], s[12:13], 0, v[136:137]
	s_addc_u32 vcc_hi, s13, 0
	s_add_i32 s97, s97, s80
	global_load_lds_dwordx4 v[232:233], off
	v_lshl_add_u64 v[234:235], vcc, 0, v[132:133]
	s_mov_b32 m0, s97
	v_lshl_add_u64 v[236:237], s[40:41], 0, v[134:135]
	global_load_lds_dwordx4 v[234:235], off
	v_lshl_add_u64 v[234:235], vcc, 0, v[136:137]
	s_add_i32 m0, s97, 0x2000
	s_nop 0
	global_load_lds_dwordx4 v[234:235], off
	v_lshl_add_u64 v[234:235], s[40:41], 0, v[130:131]
	s_mov_b32 m0, s81
	s_nop 0
	global_load_lds_dwordx4 v[234:235], off
	s_mov_b32 m0, s82
	s_nop 0
	global_load_lds_dwordx4 v[236:237], off
	s_waitcnt vmcnt(8)
	s_waitcnt lgkmcnt(0)
	s_setprio 1
	s_barrier
	v_mfma_f32_16x16x32_bf16 v[62:65], v[146:149], v[200:203], v[62:65]
	v_mfma_f32_16x16x32_bf16 v[58:61], v[164:167], v[200:203], v[58:61]
	v_mfma_f32_16x16x32_bf16 v[54:57], v[146:149], v[208:211], v[54:57]
	v_mfma_f32_16x16x32_bf16 v[50:53], v[164:167], v[208:211], v[50:53]
	v_mfma_f32_16x16x32_bf16 v[46:49], v[146:149], v[216:219], v[46:49]
	v_mfma_f32_16x16x32_bf16 v[42:45], v[164:167], v[216:219], v[42:45]
	v_mfma_f32_16x16x32_bf16 v[38:41], v[146:149], v[224:227], v[38:41]
	v_mfma_f32_16x16x32_bf16 v[34:37], v[164:167], v[224:227], v[34:37]
	v_mfma_f32_16x16x32_bf16 v[62:65], v[150:153], v[204:207], v[62:65]
	v_mfma_f32_16x16x32_bf16 v[58:61], v[172:175], v[204:207], v[58:61]
	v_mfma_f32_16x16x32_bf16 v[54:57], v[150:153], v[212:215], v[54:57]
	v_mfma_f32_16x16x32_bf16 v[50:53], v[172:175], v[212:215], v[50:53]
	v_mfma_f32_16x16x32_bf16 v[46:49], v[150:153], v[220:223], v[46:49]
	v_mfma_f32_16x16x32_bf16 v[42:45], v[172:175], v[220:223], v[42:45]
	v_mfma_f32_16x16x32_bf16 v[38:41], v[150:153], v[228:231], v[38:41]
	v_mfma_f32_16x16x32_bf16 v[34:37], v[172:175], v[228:231], v[34:37]
	s_setprio 0
	s_setprio 1
	v_mfma_f32_16x16x32_bf16 v[30:33], v[176:179], v[200:203], v[30:33]
	v_mfma_f32_16x16x32_bf16 v[26:29], v[184:187], v[200:203], v[26:29]
	v_mfma_f32_16x16x32_bf16 v[22:25], v[176:179], v[208:211], v[22:25]
	v_mfma_f32_16x16x32_bf16 v[18:21], v[184:187], v[208:211], v[18:21]
	v_mfma_f32_16x16x32_bf16 v[14:17], v[176:179], v[216:219], v[14:17]
	v_mfma_f32_16x16x32_bf16 v[10:13], v[184:187], v[216:219], v[10:13]
	v_mfma_f32_16x16x32_bf16 v[6:9], v[176:179], v[224:227], v[6:9]
	v_mfma_f32_16x16x32_bf16 v[2:5], v[184:187], v[224:227], v[2:5]
	v_mfma_f32_16x16x32_bf16 v[30:33], v[180:183], v[204:207], v[30:33]
	v_mfma_f32_16x16x32_bf16 v[26:29], v[188:191], v[204:207], v[26:29]
	v_mfma_f32_16x16x32_bf16 v[22:25], v[180:183], v[212:215], v[22:25]
	v_mfma_f32_16x16x32_bf16 v[18:21], v[188:191], v[212:215], v[18:21]
	v_mfma_f32_16x16x32_bf16 v[14:17], v[180:183], v[220:223], v[14:17]
	v_mfma_f32_16x16x32_bf16 v[10:13], v[188:191], v[220:223], v[10:13]
	v_mfma_f32_16x16x32_bf16 v[6:9], v[180:183], v[228:231], v[6:9]
	v_mfma_f32_16x16x32_bf16 v[2:5], v[188:191], v[228:231], v[2:5]
	s_setprio 0
	s_barrier
	s_add_i32 s97, 0, 0x18000
	v_add_u32_e32 v154, s97, v169
	s_add_i32 vcc_lo, 0, 0x1c000
	ds_read_b128 v[146:149], v154
	ds_read_b128 v[150:153], v154 offset:1024
	ds_read_b128 v[164:167], v154 offset:2048
	ds_read_b128 v[172:175], v154 offset:3072
	v_add_u32_e32 v154, vcc_lo, v169
	ds_read_b128 v[176:179], v154
	ds_read_b128 v[180:183], v154 offset:1024
	ds_read_b128 v[184:187], v154 offset:2048
	ds_read_b128 v[188:191], v154 offset:3072
	s_add_u32 s40, s40, 0x80000
	s_addc_u32 s41, s41, 0
	s_mov_b32 m0, s83
	v_lshl_add_u64 v[238:239], s[40:41], 0, v[130:131]
	ds_read_b128 v[200:203], v171 offset:32768
	ds_read_b128 v[204:207], v171 offset:33792
	ds_read_b128 v[208:211], v171 offset:34816
	ds_read_b128 v[212:215], v171 offset:35840
	ds_read_b128 v[216:219], v171 offset:36864
	ds_read_b128 v[220:223], v171 offset:37888
	ds_read_b128 v[224:227], v171 offset:38912
	ds_read_b128 v[228:231], v171 offset:39936
	global_load_lds_dwordx4 v[238:239], off
	v_lshl_add_u64 v[238:239], s[40:41], 0, v[134:135]
	s_mov_b32 m0, s84
	s_nop 0
	global_load_lds_dwordx4 v[238:239], off
	s_waitcnt vmcnt(8)
	s_waitcnt lgkmcnt(0)
	s_setprio 1
	s_barrier
	v_mfma_f32_16x16x32_bf16 v[126:129], v[146:149], v[200:203], v[126:129]
	v_mfma_f32_16x16x32_bf16 v[122:125], v[164:167], v[200:203], v[122:125]
	v_mfma_f32_16x16x32_bf16 v[118:121], v[146:149], v[208:211], v[118:121]
	v_mfma_f32_16x16x32_bf16 v[114:117], v[164:167], v[208:211], v[114:117]
	v_mfma_f32_16x16x32_bf16 v[110:113], v[146:149], v[216:219], v[110:113]
	v_mfma_f32_16x16x32_bf16 v[106:109], v[164:167], v[216:219], v[106:109]
	v_mfma_f32_16x16x32_bf16 v[102:105], v[146:149], v[224:227], v[102:105]
	v_mfma_f32_16x16x32_bf16 v[98:101], v[164:167], v[224:227], v[98:101]
	v_mfma_f32_16x16x32_bf16 v[126:129], v[150:153], v[204:207], v[126:129]
	v_mfma_f32_16x16x32_bf16 v[122:125], v[172:175], v[204:207], v[122:125]
	v_mfma_f32_16x16x32_bf16 v[118:121], v[150:153], v[212:215], v[118:121]
	v_mfma_f32_16x16x32_bf16 v[114:117], v[172:175], v[212:215], v[114:117]
	v_mfma_f32_16x16x32_bf16 v[110:113], v[150:153], v[220:223], v[110:113]
	v_mfma_f32_16x16x32_bf16 v[106:109], v[172:175], v[220:223], v[106:109]
	v_mfma_f32_16x16x32_bf16 v[102:105], v[150:153], v[228:231], v[102:105]
	v_mfma_f32_16x16x32_bf16 v[98:101], v[172:175], v[228:231], v[98:101]
	s_setprio 0
	s_setprio 1
	v_mfma_f32_16x16x32_bf16 v[94:97], v[176:179], v[200:203], v[94:97]
	v_mfma_f32_16x16x32_bf16 v[90:93], v[184:187], v[200:203], v[90:93]
	v_mfma_f32_16x16x32_bf16 v[86:89], v[176:179], v[208:211], v[86:89]
	v_mfma_f32_16x16x32_bf16 v[82:85], v[184:187], v[208:211], v[82:85]
	v_mfma_f32_16x16x32_bf16 v[78:81], v[176:179], v[216:219], v[78:81]
	v_mfma_f32_16x16x32_bf16 v[74:77], v[184:187], v[216:219], v[74:77]
	v_mfma_f32_16x16x32_bf16 v[70:73], v[176:179], v[224:227], v[70:73]
	v_mfma_f32_16x16x32_bf16 v[66:69], v[184:187], v[224:227], v[66:69]
	v_mfma_f32_16x16x32_bf16 v[94:97], v[180:183], v[204:207], v[94:97]
	v_mfma_f32_16x16x32_bf16 v[90:93], v[188:191], v[204:207], v[90:93]
	v_mfma_f32_16x16x32_bf16 v[86:89], v[180:183], v[212:215], v[86:89]
	v_mfma_f32_16x16x32_bf16 v[82:85], v[188:191], v[212:215], v[82:85]
	v_mfma_f32_16x16x32_bf16 v[78:81], v[180:183], v[220:223], v[78:81]
	v_mfma_f32_16x16x32_bf16 v[74:77], v[188:191], v[220:223], v[74:77]
	v_mfma_f32_16x16x32_bf16 v[70:73], v[180:183], v[228:231], v[70:73]
	v_mfma_f32_16x16x32_bf16 v[66:69], v[188:191], v[228:231], v[66:69]
	s_setprio 0
	s_barrier
	s_add_i32 s40, s97, s80
	v_lshl_add_u64 v[196:197], v[196:197], 0, s[34:35]
	s_mov_b32 m0, s40
	ds_read_b128 v[200:203], v171 offset:49152
	ds_read_b128 v[204:207], v171 offset:50176
	ds_read_b128 v[208:211], v171 offset:51200
	ds_read_b128 v[212:215], v171 offset:52224
	ds_read_b128 v[216:219], v171 offset:53248
	ds_read_b128 v[220:223], v171 offset:54272
	ds_read_b128 v[224:227], v171 offset:55296
	ds_read_b128 v[228:231], v171 offset:56320
	global_load_lds_dwordx4 v[196:197], off
	s_add_i32 m0, s40, 0x2000
	s_add_u32 s12, s12, 0x80080
	v_lshl_add_u64 v[196:197], v[232:233], 0, s[34:35]
	s_addc_u32 s13, s13, 0
	s_add_i32 s40, vcc_lo, s80
	global_load_lds_dwordx4 v[196:197], off
	v_lshl_add_u64 v[196:197], s[12:13], 0, v[132:133]
	s_mov_b32 m0, s40
	s_nop 0
	global_load_lds_dwordx4 v[196:197], off
	v_lshl_add_u64 v[196:197], s[12:13], 0, v[136:137]
	s_add_i32 m0, s40, 0x2000
	s_nop 0
	global_load_lds_dwordx4 v[196:197], off
	v_lshl_add_u64 v[196:197], v[234:235], 0, s[34:35]
	s_mov_b32 m0, s85
	s_nop 0
	global_load_lds_dwordx4 v[196:197], off
	v_lshl_add_u64 v[196:197], v[236:237], 0, s[34:35]
	s_mov_b32 m0, s86
	s_nop 0
	global_load_lds_dwordx4 v[196:197], off
	s_waitcnt vmcnt(8)
	s_waitcnt lgkmcnt(0)
	s_setprio 1
	s_barrier
	v_mfma_f32_16x16x32_bf16 v[62:65], v[146:149], v[200:203], v[62:65]
	v_mfma_f32_16x16x32_bf16 v[58:61], v[164:167], v[200:203], v[58:61]
	v_mfma_f32_16x16x32_bf16 v[54:57], v[146:149], v[208:211], v[54:57]
	v_mfma_f32_16x16x32_bf16 v[50:53], v[164:167], v[208:211], v[50:53]
	v_mfma_f32_16x16x32_bf16 v[46:49], v[146:149], v[216:219], v[46:49]
	v_mfma_f32_16x16x32_bf16 v[42:45], v[164:167], v[216:219], v[42:45]
	v_mfma_f32_16x16x32_bf16 v[38:41], v[146:149], v[224:227], v[38:41]
	v_mfma_f32_16x16x32_bf16 v[34:37], v[164:167], v[224:227], v[34:37]
	v_mfma_f32_16x16x32_bf16 v[62:65], v[150:153], v[204:207], v[62:65]
	v_mfma_f32_16x16x32_bf16 v[58:61], v[172:175], v[204:207], v[58:61]
	v_mfma_f32_16x16x32_bf16 v[54:57], v[150:153], v[212:215], v[54:57]
	v_mfma_f32_16x16x32_bf16 v[50:53], v[172:175], v[212:215], v[50:53]
	v_mfma_f32_16x16x32_bf16 v[46:49], v[150:153], v[220:223], v[46:49]
	v_mfma_f32_16x16x32_bf16 v[42:45], v[172:175], v[220:223], v[42:45]
	v_mfma_f32_16x16x32_bf16 v[38:41], v[150:153], v[228:231], v[38:41]
	v_mfma_f32_16x16x32_bf16 v[34:37], v[172:175], v[228:231], v[34:37]
	s_setprio 0
	s_setprio 1
	v_mfma_f32_16x16x32_bf16 v[30:33], v[176:179], v[200:203], v[30:33]
	v_mfma_f32_16x16x32_bf16 v[26:29], v[184:187], v[200:203], v[26:29]
	v_mfma_f32_16x16x32_bf16 v[22:25], v[176:179], v[208:211], v[22:25]
	v_mfma_f32_16x16x32_bf16 v[18:21], v[184:187], v[208:211], v[18:21]
	v_mfma_f32_16x16x32_bf16 v[14:17], v[176:179], v[216:219], v[14:17]
	v_mfma_f32_16x16x32_bf16 v[10:13], v[184:187], v[216:219], v[10:13]
	v_mfma_f32_16x16x32_bf16 v[6:9], v[176:179], v[224:227], v[6:9]
	v_mfma_f32_16x16x32_bf16 v[2:5], v[184:187], v[224:227], v[2:5]
	v_mfma_f32_16x16x32_bf16 v[30:33], v[180:183], v[204:207], v[30:33]
	v_mfma_f32_16x16x32_bf16 v[26:29], v[188:191], v[204:207], v[26:29]
	v_mfma_f32_16x16x32_bf16 v[22:25], v[180:183], v[212:215], v[22:25]
	v_mfma_f32_16x16x32_bf16 v[18:21], v[188:191], v[212:215], v[18:21]
	v_mfma_f32_16x16x32_bf16 v[14:17], v[180:183], v[220:223], v[14:17]
	v_mfma_f32_16x16x32_bf16 v[10:13], v[188:191], v[220:223], v[10:13]
	v_mfma_f32_16x16x32_bf16 v[6:9], v[180:183], v[228:231], v[6:9]
	v_mfma_f32_16x16x32_bf16 v[2:5], v[188:191], v[228:231], v[2:5]
	s_setprio 0
	s_barrier
	s_add_i32 s96, s96, 2
	s_add_u32 s10, s10, 0x100
	s_addc_u32 s11, s11, 0
	s_cmp_gt_u32 s96, 29
	s_cbranch_scc0 .LBB0_290
	s_and_b64 vcc, exec, s[56:57]
	s_cbranch_vccz .LBB0_293
	s_barrier

.LBB0_473:
	s_add_u32 s64, s56, s10
	s_addc_u32 s65, s57, s11
	s_add_u32 s64, s64, 0x100
	s_addc_u32 s65, s65, 0
	s_add_u32 vcc_lo, s93, s10
	s_addc_u32 vcc_hi, s94, s11
	s_add_i32 s16, 0, 0x10000
	s_cmpk_eq_i32 s10, 0xf00
	s_cselect_b32 s67, s55, s65
	s_cselect_b32 s66, s95, s64
	s_cselect_b32 s65, s53, vcc_hi
	s_cselect_b32 s64, s96, vcc_lo
	s_add_i32 s24, 0, 0x14000
	v_add_u32_e32 v146, s16, v197
	v_add_u32_e32 v182, s24, v197
	ds_read_b128 v[134:137], v146
	ds_read_b128 v[138:141], v146 offset:1024
	ds_read_b128 v[142:145], v146 offset:2048
	ds_read_b128 v[146:149], v146 offset:3072
	ds_read_b128 v[150:153], v182
	ds_read_b128 v[174:177], v182 offset:1024
	ds_read_b128 v[178:181], v182 offset:2048
	ds_read_b128 v[182:185], v182 offset:3072
	v_lshl_add_u64 v[190:191], v[130:131], 0, s[10:11]
	s_add_i32 m0, s80, 0xc000
	ds_read_b128 v[186:189], v200
	ds_read_b128 v[202:205], v200 offset:1024
	ds_read_b128 v[206:209], v200 offset:2048
	ds_read_b128 v[210:213], v200 offset:3072
	ds_read_b128 v[214:217], v200 offset:4096
	ds_read_b128 v[218:221], v200 offset:5120
	ds_read_b128 v[222:225], v200 offset:6144
	ds_read_b128 v[226:229], v200 offset:7168
	global_load_lds_dwordx4 v[190:191], off
	v_lshl_add_u64 v[190:191], v[132:133], 0, s[10:11]
	s_add_i32 m0, s80, 0xe000
	s_nop 0
	global_load_lds_dwordx4 v[190:191], off
	s_waitcnt vmcnt(8)
	s_waitcnt lgkmcnt(0)
	s_setprio 1
	s_barrier
	v_mfma_f32_16x16x32_bf16 v[126:129], v[134:137], v[186:189], v[126:129]
	v_mfma_f32_16x16x32_bf16 v[122:125], v[142:145], v[186:189], v[122:125]
	v_mfma_f32_16x16x32_bf16 v[118:121], v[134:137], v[206:209], v[118:121]
	v_mfma_f32_16x16x32_bf16 v[114:117], v[142:145], v[206:209], v[114:117]
	v_mfma_f32_16x16x32_bf16 v[110:113], v[134:137], v[214:217], v[110:113]
	v_mfma_f32_16x16x32_bf16 v[106:109], v[142:145], v[214:217], v[106:109]
	v_mfma_f32_16x16x32_bf16 v[102:105], v[134:137], v[222:225], v[102:105]
	v_mfma_f32_16x16x32_bf16 v[98:101], v[142:145], v[222:225], v[98:101]
	v_mfma_f32_16x16x32_bf16 v[126:129], v[138:141], v[202:205], v[126:129]
	v_mfma_f32_16x16x32_bf16 v[122:125], v[146:149], v[202:205], v[122:125]
	v_mfma_f32_16x16x32_bf16 v[118:121], v[138:141], v[210:213], v[118:121]
	v_mfma_f32_16x16x32_bf16 v[114:117], v[146:149], v[210:213], v[114:117]
	v_mfma_f32_16x16x32_bf16 v[110:113], v[138:141], v[218:221], v[110:113]
	v_mfma_f32_16x16x32_bf16 v[106:109], v[146:149], v[218:221], v[106:109]
	v_mfma_f32_16x16x32_bf16 v[102:105], v[138:141], v[226:229], v[102:105]
	v_mfma_f32_16x16x32_bf16 v[98:101], v[146:149], v[226:229], v[98:101]
	s_setprio 0
	s_setprio 1
	v_mfma_f32_16x16x32_bf16 v[94:97], v[150:153], v[186:189], v[94:97]
	v_mfma_f32_16x16x32_bf16 v[90:93], v[178:181], v[186:189], v[90:93]
	v_mfma_f32_16x16x32_bf16 v[86:89], v[150:153], v[206:209], v[86:89]
	v_mfma_f32_16x16x32_bf16 v[82:85], v[178:181], v[206:209], v[82:85]
	v_mfma_f32_16x16x32_bf16 v[78:81], v[150:153], v[214:217], v[78:81]
	v_mfma_f32_16x16x32_bf16 v[74:77], v[178:181], v[214:217], v[74:77]
	v_mfma_f32_16x16x32_bf16 v[70:73], v[150:153], v[222:225], v[70:73]
	v_mfma_f32_16x16x32_bf16 v[66:69], v[178:181], v[222:225], v[66:69]
	v_mfma_f32_16x16x32_bf16 v[94:97], v[174:177], v[202:205], v[94:97]
	v_mfma_f32_16x16x32_bf16 v[90:93], v[182:185], v[202:205], v[90:93]
	v_mfma_f32_16x16x32_bf16 v[86:89], v[174:177], v[210:213], v[86:89]
	v_mfma_f32_16x16x32_bf16 v[82:85], v[182:185], v[210:213], v[82:85]
	v_mfma_f32_16x16x32_bf16 v[78:81], v[174:177], v[218:221], v[78:81]
	v_mfma_f32_16x16x32_bf16 v[74:77], v[182:185], v[218:221], v[74:77]
	v_mfma_f32_16x16x32_bf16 v[70:73], v[174:177], v[226:229], v[70:73]
	v_mfma_f32_16x16x32_bf16 v[66:69], v[182:185], v[226:229], v[66:69]
	s_setprio 0
	s_barrier
	s_add_i32 s16, s16, s30
	v_lshl_add_u64 v[190:191], s[64:65], 0, v[154:155]
	s_mov_b32 m0, s16
	ds_read_b128 v[186:189], v200 offset:16384
	ds_read_b128 v[202:205], v200 offset:17408
	ds_read_b128 v[206:209], v200 offset:18432
	ds_read_b128 v[210:213], v200 offset:19456
	ds_read_b128 v[214:217], v200 offset:20480
	ds_read_b128 v[218:221], v200 offset:21504
	ds_read_b128 v[222:225], v200 offset:22528
	ds_read_b128 v[226:229], v200 offset:23552
	global_load_lds_dwordx4 v[190:191], off
	s_add_i32 m0, s16, 0x2000
	s_add_u32 vcc_lo, s64, 0x80000
	v_lshl_add_u64 v[230:231], s[64:65], 0, v[164:165]
	s_addc_u32 vcc_hi, s65, 0
	s_add_i32 s16, s24, s30
	global_load_lds_dwordx4 v[230:231], off
	v_lshl_add_u64 v[232:233], vcc, 0, v[154:155]
	s_mov_b32 m0, s16
	v_lshl_add_u64 v[234:235], s[66:67], 0, v[166:167]
	global_load_lds_dwordx4 v[232:233], off
	v_lshl_add_u64 v[232:233], vcc, 0, v[164:165]
	s_add_i32 m0, s16, 0x2000
	s_nop 0
	global_load_lds_dwordx4 v[232:233], off
	v_lshl_add_u64 v[232:233], s[66:67], 0, v[168:169]
	s_mov_b32 m0, s80
	s_nop 0
	global_load_lds_dwordx4 v[232:233], off
	s_mov_b32 m0, s81
	s_nop 0
	global_load_lds_dwordx4 v[234:235], off
	s_waitcnt vmcnt(8)
	s_waitcnt lgkmcnt(0)
	s_setprio 1
	s_barrier
	v_mfma_f32_16x16x32_bf16 v[62:65], v[134:137], v[186:189], v[62:65]
	v_mfma_f32_16x16x32_bf16 v[58:61], v[142:145], v[186:189], v[58:61]
	v_mfma_f32_16x16x32_bf16 v[54:57], v[134:137], v[206:209], v[54:57]
	v_mfma_f32_16x16x32_bf16 v[50:53], v[142:145], v[206:209], v[50:53]
	v_mfma_f32_16x16x32_bf16 v[46:49], v[134:137], v[214:217], v[46:49]
	v_mfma_f32_16x16x32_bf16 v[42:45], v[142:145], v[214:217], v[42:45]
	v_mfma_f32_16x16x32_bf16 v[38:41], v[134:137], v[222:225], v[38:41]
	v_mfma_f32_16x16x32_bf16 v[34:37], v[142:145], v[222:225], v[34:37]
	v_mfma_f32_16x16x32_bf16 v[62:65], v[138:141], v[202:205], v[62:65]
	v_mfma_f32_16x16x32_bf16 v[58:61], v[146:149], v[202:205], v[58:61]
	v_mfma_f32_16x16x32_bf16 v[54:57], v[138:141], v[210:213], v[54:57]
	v_mfma_f32_16x16x32_bf16 v[50:53], v[146:149], v[210:213], v[50:53]
	v_mfma_f32_16x16x32_bf16 v[46:49], v[138:141], v[218:221], v[46:49]
	v_mfma_f32_16x16x32_bf16 v[42:45], v[146:149], v[218:221], v[42:45]
	v_mfma_f32_16x16x32_bf16 v[38:41], v[138:141], v[226:229], v[38:41]
	v_mfma_f32_16x16x32_bf16 v[34:37], v[146:149], v[226:229], v[34:37]
	s_setprio 0
	s_setprio 1
	v_mfma_f32_16x16x32_bf16 v[30:33], v[150:153], v[186:189], v[30:33]
	v_mfma_f32_16x16x32_bf16 v[26:29], v[178:181], v[186:189], v[26:29]
	v_mfma_f32_16x16x32_bf16 v[22:25], v[150:153], v[206:209], v[22:25]
	v_mfma_f32_16x16x32_bf16 v[18:21], v[178:181], v[206:209], v[18:21]
	v_mfma_f32_16x16x32_bf16 v[14:17], v[150:153], v[214:217], v[14:17]
	v_mfma_f32_16x16x32_bf16 v[10:13], v[178:181], v[214:217], v[10:13]
	v_mfma_f32_16x16x32_bf16 v[6:9], v[150:153], v[222:225], v[6:9]
	v_mfma_f32_16x16x32_bf16 v[2:5], v[178:181], v[222:225], v[2:5]
	v_mfma_f32_16x16x32_bf16 v[30:33], v[174:177], v[202:205], v[30:33]
	v_mfma_f32_16x16x32_bf16 v[26:29], v[182:185], v[202:205], v[26:29]
	v_mfma_f32_16x16x32_bf16 v[22:25], v[174:177], v[210:213], v[22:25]
	v_mfma_f32_16x16x32_bf16 v[18:21], v[182:185], v[210:213], v[18:21]
	v_mfma_f32_16x16x32_bf16 v[14:17], v[174:177], v[218:221], v[14:17]
	v_mfma_f32_16x16x32_bf16 v[10:13], v[182:185], v[218:221], v[10:13]
	v_mfma_f32_16x16x32_bf16 v[6:9], v[174:177], v[226:229], v[6:9]
	v_mfma_f32_16x16x32_bf16 v[2:5], v[182:185], v[226:229], v[2:5]
	s_setprio 0
	s_barrier
	s_add_i32 s16, 0, 0x18000
	s_add_i32 s24, 0, 0x1c000
	v_add_u32_e32 v146, s16, v197
	v_add_u32_e32 v182, s24, v197
	ds_read_b128 v[134:137], v146
	ds_read_b128 v[138:141], v146 offset:1024
	ds_read_b128 v[142:145], v146 offset:2048
	ds_read_b128 v[146:149], v146 offset:3072
	ds_read_b128 v[150:153], v182
	ds_read_b128 v[174:177], v182 offset:1024
	ds_read_b128 v[178:181], v182 offset:2048
	ds_read_b128 v[182:185], v182 offset:3072
	s_add_u32 s66, s66, 0x80000
	s_addc_u32 s67, s67, 0
	s_mov_b32 m0, s82
	v_lshl_add_u64 v[236:237], s[66:67], 0, v[168:169]
	ds_read_b128 v[186:189], v200 offset:32768
	ds_read_b128 v[202:205], v200 offset:33792
	ds_read_b128 v[206:209], v200 offset:34816
	ds_read_b128 v[210:213], v200 offset:35840
	ds_read_b128 v[214:217], v200 offset:36864
	ds_read_b128 v[218:221], v200 offset:37888
	ds_read_b128 v[222:225], v200 offset:38912
	ds_read_b128 v[226:229], v200 offset:39936
	global_load_lds_dwordx4 v[236:237], off
	v_lshl_add_u64 v[236:237], s[66:67], 0, v[166:167]
	s_mov_b32 m0, s83
	s_nop 0
	global_load_lds_dwordx4 v[236:237], off
	s_waitcnt vmcnt(8)
	s_waitcnt lgkmcnt(0)
	s_setprio 1
	s_barrier
	v_mfma_f32_16x16x32_bf16 v[126:129], v[134:137], v[186:189], v[126:129]
	v_mfma_f32_16x16x32_bf16 v[122:125], v[142:145], v[186:189], v[122:125]
	v_mfma_f32_16x16x32_bf16 v[118:121], v[134:137], v[206:209], v[118:121]
	v_mfma_f32_16x16x32_bf16 v[114:117], v[142:145], v[206:209], v[114:117]
	v_mfma_f32_16x16x32_bf16 v[110:113], v[134:137], v[214:217], v[110:113]
	v_mfma_f32_16x16x32_bf16 v[106:109], v[142:145], v[214:217], v[106:109]
	v_mfma_f32_16x16x32_bf16 v[102:105], v[134:137], v[222:225], v[102:105]
	v_mfma_f32_16x16x32_bf16 v[98:101], v[142:145], v[222:225], v[98:101]
	v_mfma_f32_16x16x32_bf16 v[126:129], v[138:141], v[202:205], v[126:129]
	v_mfma_f32_16x16x32_bf16 v[122:125], v[146:149], v[202:205], v[122:125]
	v_mfma_f32_16x16x32_bf16 v[118:121], v[138:141], v[210:213], v[118:121]
	v_mfma_f32_16x16x32_bf16 v[114:117], v[146:149], v[210:213], v[114:117]
	v_mfma_f32_16x16x32_bf16 v[110:113], v[138:141], v[218:221], v[110:113]
	v_mfma_f32_16x16x32_bf16 v[106:109], v[146:149], v[218:221], v[106:109]
	v_mfma_f32_16x16x32_bf16 v[102:105], v[138:141], v[226:229], v[102:105]
	v_mfma_f32_16x16x32_bf16 v[98:101], v[146:149], v[226:229], v[98:101]
	s_setprio 0
	s_setprio 1
	v_mfma_f32_16x16x32_bf16 v[94:97], v[150:153], v[186:189], v[94:97]
	v_mfma_f32_16x16x32_bf16 v[90:93], v[178:181], v[186:189], v[90:93]
	v_mfma_f32_16x16x32_bf16 v[86:89], v[150:153], v[206:209], v[86:89]
	v_mfma_f32_16x16x32_bf16 v[82:85], v[178:181], v[206:209], v[82:85]
	v_mfma_f32_16x16x32_bf16 v[78:81], v[150:153], v[214:217], v[78:81]
	v_mfma_f32_16x16x32_bf16 v[74:77], v[178:181], v[214:217], v[74:77]
	v_mfma_f32_16x16x32_bf16 v[70:73], v[150:153], v[222:225], v[70:73]
	v_mfma_f32_16x16x32_bf16 v[66:69], v[178:181], v[222:225], v[66:69]
	v_mfma_f32_16x16x32_bf16 v[94:97], v[174:177], v[202:205], v[94:97]
	v_mfma_f32_16x16x32_bf16 v[90:93], v[182:185], v[202:205], v[90:93]
	v_mfma_f32_16x16x32_bf16 v[86:89], v[174:177], v[210:213], v[86:89]
	v_mfma_f32_16x16x32_bf16 v[82:85], v[182:185], v[210:213], v[82:85]
	v_mfma_f32_16x16x32_bf16 v[78:81], v[174:177], v[218:221], v[78:81]
	v_mfma_f32_16x16x32_bf16 v[74:77], v[182:185], v[218:221], v[74:77]
	v_mfma_f32_16x16x32_bf16 v[70:73], v[174:177], v[226:229], v[70:73]
	v_mfma_f32_16x16x32_bf16 v[66:69], v[182:185], v[226:229], v[66:69]
	s_setprio 0
	s_barrier
	s_add_i32 s16, s16, s30
	v_lshl_add_u64 v[190:191], v[190:191], 0, s[34:35]
	s_mov_b32 m0, s16
	ds_read_b128 v[186:189], v200 offset:49152
	ds_read_b128 v[202:205], v200 offset:50176
	ds_read_b128 v[206:209], v200 offset:51200
	ds_read_b128 v[210:213], v200 offset:52224
	ds_read_b128 v[214:217], v200 offset:53248
	ds_read_b128 v[218:221], v200 offset:54272
	ds_read_b128 v[222:225], v200 offset:55296
	ds_read_b128 v[226:229], v200 offset:56320
	global_load_lds_dwordx4 v[190:191], off
	s_add_i32 m0, s16, 0x2000
	s_add_u32 s64, s64, 0x80080
	v_lshl_add_u64 v[190:191], v[230:231], 0, s[34:35]
	s_addc_u32 s65, s65, 0
	s_add_i32 s16, s24, s30
	global_load_lds_dwordx4 v[190:191], off
	v_lshl_add_u64 v[190:191], s[64:65], 0, v[154:155]
	s_mov_b32 m0, s16
	s_nop 0
	global_load_lds_dwordx4 v[190:191], off
	v_lshl_add_u64 v[190:191], s[64:65], 0, v[164:165]
	s_add_i32 m0, s16, 0x2000
	s_nop 0
	global_load_lds_dwordx4 v[190:191], off
	v_lshl_add_u64 v[190:191], v[232:233], 0, s[34:35]
	s_mov_b32 m0, s84
	s_nop 0
	global_load_lds_dwordx4 v[190:191], off
	v_lshl_add_u64 v[190:191], v[234:235], 0, s[34:35]
	s_mov_b32 m0, s85
	s_nop 0
	global_load_lds_dwordx4 v[190:191], off
	s_waitcnt vmcnt(8)
	s_waitcnt lgkmcnt(0)
	s_setprio 1
	s_barrier
	v_mfma_f32_16x16x32_bf16 v[62:65], v[134:137], v[186:189], v[62:65]
	v_mfma_f32_16x16x32_bf16 v[58:61], v[142:145], v[186:189], v[58:61]
	v_mfma_f32_16x16x32_bf16 v[54:57], v[134:137], v[206:209], v[54:57]
	v_mfma_f32_16x16x32_bf16 v[50:53], v[142:145], v[206:209], v[50:53]
	v_mfma_f32_16x16x32_bf16 v[46:49], v[134:137], v[214:217], v[46:49]
	v_mfma_f32_16x16x32_bf16 v[42:45], v[142:145], v[214:217], v[42:45]
	v_mfma_f32_16x16x32_bf16 v[38:41], v[134:137], v[222:225], v[38:41]
	v_mfma_f32_16x16x32_bf16 v[34:37], v[142:145], v[222:225], v[34:37]
	v_mfma_f32_16x16x32_bf16 v[62:65], v[138:141], v[202:205], v[62:65]
	v_mfma_f32_16x16x32_bf16 v[58:61], v[146:149], v[202:205], v[58:61]
	v_mfma_f32_16x16x32_bf16 v[54:57], v[138:141], v[210:213], v[54:57]
	v_mfma_f32_16x16x32_bf16 v[50:53], v[146:149], v[210:213], v[50:53]
	v_mfma_f32_16x16x32_bf16 v[46:49], v[138:141], v[218:221], v[46:49]
	v_mfma_f32_16x16x32_bf16 v[42:45], v[146:149], v[218:221], v[42:45]
	v_mfma_f32_16x16x32_bf16 v[38:41], v[138:141], v[226:229], v[38:41]
	v_mfma_f32_16x16x32_bf16 v[34:37], v[146:149], v[226:229], v[34:37]
	s_setprio 0
	s_setprio 1
	v_mfma_f32_16x16x32_bf16 v[30:33], v[150:153], v[186:189], v[30:33]
	v_mfma_f32_16x16x32_bf16 v[26:29], v[178:181], v[186:189], v[26:29]
	v_mfma_f32_16x16x32_bf16 v[22:25], v[150:153], v[206:209], v[22:25]
	v_mfma_f32_16x16x32_bf16 v[18:21], v[178:181], v[206:209], v[18:21]
	v_mfma_f32_16x16x32_bf16 v[14:17], v[150:153], v[214:217], v[14:17]
	v_mfma_f32_16x16x32_bf16 v[10:13], v[178:181], v[214:217], v[10:13]
	v_mfma_f32_16x16x32_bf16 v[6:9], v[150:153], v[222:225], v[6:9]
	v_mfma_f32_16x16x32_bf16 v[2:5], v[178:181], v[222:225], v[2:5]
	v_mfma_f32_16x16x32_bf16 v[30:33], v[174:177], v[202:205], v[30:33]
	v_mfma_f32_16x16x32_bf16 v[26:29], v[182:185], v[202:205], v[26:29]
	v_mfma_f32_16x16x32_bf16 v[22:25], v[174:177], v[210:213], v[22:25]
	v_mfma_f32_16x16x32_bf16 v[18:21], v[182:185], v[210:213], v[18:21]
	v_mfma_f32_16x16x32_bf16 v[14:17], v[174:177], v[218:221], v[14:17]
	v_mfma_f32_16x16x32_bf16 v[10:13], v[182:185], v[218:221], v[10:13]
	v_mfma_f32_16x16x32_bf16 v[6:9], v[174:177], v[226:229], v[6:9]
	v_mfma_f32_16x16x32_bf16 v[2:5], v[182:185], v[226:229], v[2:5]
	s_setprio 0
	s_barrier
	s_add_i32 s97, s97, 2
	s_add_u32 s10, s10, 0x100
	s_addc_u32 s11, s11, 0
	s_cmp_gt_u32 s97, 29
	s_cbranch_scc0 .LBB0_473
	s_and_b64 vcc, exec, s[46:47]
	s_cbranch_vccz .LBB0_476
	s_barrier

.LBB0_623:
	s_add_u32 s8, s52, s0
	s_addc_u32 s9, s53, s1
	s_add_u32 s8, s8, 0x100
	s_addc_u32 s9, s9, 0
	s_add_u32 s55, s76, s0
	s_addc_u32 s78, s77, s1
	s_add_i32 s79, 0, 0x10000
	s_cmpk_eq_i32 s0, 0xf00
	s_cselect_b32 s11, s12, s9
	s_cselect_b32 s10, s13, s8
	s_cselect_b32 s9, s26, s78
	s_cselect_b32 s8, s27, s55
	s_add_i32 s55, 0, 0x14000
	v_add_u32_e32 v148, s79, v204
	v_add_u32_e32 v186, s55, v204
	ds_read_b128 v[136:139], v148
	ds_read_b128 v[140:143], v148 offset:1024
	ds_read_b128 v[144:147], v148 offset:2048
	ds_read_b128 v[148:151], v148 offset:3072
	ds_read_b128 v[152:155], v186
	ds_read_b128 v[156:159], v186 offset:1024
	ds_read_b128 v[160:163], v186 offset:2048
	ds_read_b128 v[186:189], v186 offset:3072
	v_lshl_add_u64 v[230:231], v[132:133], 0, s[0:1]
	s_add_i32 m0, s25, 0xc000
	ds_read_b128 v[190:193], v205
	ds_read_b128 v[194:197], v205 offset:1024
	ds_read_b128 v[206:209], v205 offset:2048
	ds_read_b128 v[210:213], v205 offset:3072
	ds_read_b128 v[214:217], v205 offset:4096
	ds_read_b128 v[218:221], v205 offset:5120
	ds_read_b128 v[222:225], v205 offset:6144
	ds_read_b128 v[226:229], v205 offset:7168
	global_load_lds_dwordx4 v[230:231], off
	v_lshl_add_u64 v[230:231], v[134:135], 0, s[0:1]
	s_add_i32 m0, s25, 0xe000
	s_nop 0
	global_load_lds_dwordx4 v[230:231], off
	s_waitcnt vmcnt(8)
	s_waitcnt lgkmcnt(0)
	s_setprio 1
	s_barrier
	v_mfma_f32_16x16x32_bf16 v[128:131], v[136:139], v[190:193], v[128:131]
	v_mfma_f32_16x16x32_bf16 v[124:127], v[144:147], v[190:193], v[124:127]
	v_mfma_f32_16x16x32_bf16 v[120:123], v[136:139], v[206:209], v[120:123]
	v_mfma_f32_16x16x32_bf16 v[116:119], v[144:147], v[206:209], v[116:119]
	v_mfma_f32_16x16x32_bf16 v[112:115], v[136:139], v[214:217], v[112:115]
	v_mfma_f32_16x16x32_bf16 v[108:111], v[144:147], v[214:217], v[108:111]
	v_mfma_f32_16x16x32_bf16 v[104:107], v[136:139], v[222:225], v[104:107]
	v_mfma_f32_16x16x32_bf16 v[100:103], v[144:147], v[222:225], v[100:103]
	v_mfma_f32_16x16x32_bf16 v[128:131], v[140:143], v[194:197], v[128:131]
	v_mfma_f32_16x16x32_bf16 v[124:127], v[148:151], v[194:197], v[124:127]
	v_mfma_f32_16x16x32_bf16 v[120:123], v[140:143], v[210:213], v[120:123]
	v_mfma_f32_16x16x32_bf16 v[116:119], v[148:151], v[210:213], v[116:119]
	v_mfma_f32_16x16x32_bf16 v[112:115], v[140:143], v[218:221], v[112:115]
	v_mfma_f32_16x16x32_bf16 v[108:111], v[148:151], v[218:221], v[108:111]
	v_mfma_f32_16x16x32_bf16 v[104:107], v[140:143], v[226:229], v[104:107]
	v_mfma_f32_16x16x32_bf16 v[100:103], v[148:151], v[226:229], v[100:103]
	s_setprio 0
	s_setprio 1
	v_mfma_f32_16x16x32_bf16 v[96:99], v[152:155], v[190:193], v[96:99]
	v_mfma_f32_16x16x32_bf16 v[92:95], v[160:163], v[190:193], v[92:95]
	v_mfma_f32_16x16x32_bf16 v[88:91], v[152:155], v[206:209], v[88:91]
	v_mfma_f32_16x16x32_bf16 v[84:87], v[160:163], v[206:209], v[84:87]
	v_mfma_f32_16x16x32_bf16 v[80:83], v[152:155], v[214:217], v[80:83]
	v_mfma_f32_16x16x32_bf16 v[76:79], v[160:163], v[214:217], v[76:79]
	v_mfma_f32_16x16x32_bf16 v[72:75], v[152:155], v[222:225], v[72:75]
	v_mfma_f32_16x16x32_bf16 v[68:71], v[160:163], v[222:225], v[68:71]
	v_mfma_f32_16x16x32_bf16 v[96:99], v[156:159], v[194:197], v[96:99]
	v_mfma_f32_16x16x32_bf16 v[92:95], v[186:189], v[194:197], v[92:95]
	v_mfma_f32_16x16x32_bf16 v[88:91], v[156:159], v[210:213], v[88:91]
	v_mfma_f32_16x16x32_bf16 v[84:87], v[186:189], v[210:213], v[84:87]
	v_mfma_f32_16x16x32_bf16 v[80:83], v[156:159], v[218:221], v[80:83]
	v_mfma_f32_16x16x32_bf16 v[76:79], v[186:189], v[218:221], v[76:79]
	v_mfma_f32_16x16x32_bf16 v[72:75], v[156:159], v[226:229], v[72:75]
	v_mfma_f32_16x16x32_bf16 v[68:71], v[186:189], v[226:229], v[68:71]
	s_setprio 0
	s_barrier
	s_add_i32 s78, s79, s24
	v_lshl_add_u64 v[230:231], s[8:9], 0, v[170:171]
	s_mov_b32 m0, s78
	ds_read_b128 v[190:193], v205 offset:16384
	ds_read_b128 v[194:197], v205 offset:17408
	ds_read_b128 v[206:209], v205 offset:18432
	ds_read_b128 v[210:213], v205 offset:19456
	ds_read_b128 v[214:217], v205 offset:20480
	ds_read_b128 v[218:221], v205 offset:21504
	ds_read_b128 v[222:225], v205 offset:22528
	ds_read_b128 v[226:229], v205 offset:23552
	global_load_lds_dwordx4 v[230:231], off
	s_add_i32 m0, s78, 0x2000
	s_add_u32 s78, s8, 0x80000
	v_lshl_add_u64 v[232:233], s[8:9], 0, v[174:175]
	s_addc_u32 s79, s9, 0
	s_add_i32 s55, s55, s24
	global_load_lds_dwordx4 v[232:233], off
	v_lshl_add_u64 v[234:235], s[78:79], 0, v[170:171]
	s_mov_b32 m0, s55
	v_lshl_add_u64 v[236:237], s[10:11], 0, v[172:173]
	global_load_lds_dwordx4 v[234:235], off
	v_lshl_add_u64 v[234:235], s[78:79], 0, v[174:175]
	s_add_i32 m0, s55, 0x2000
	s_nop 0
	global_load_lds_dwordx4 v[234:235], off
	v_lshl_add_u64 v[234:235], s[10:11], 0, v[168:169]
	s_mov_b32 m0, s25
	s_nop 0
	global_load_lds_dwordx4 v[234:235], off
	s_mov_b32 m0, s30
	s_nop 0
	global_load_lds_dwordx4 v[236:237], off
	s_waitcnt vmcnt(8)
	s_waitcnt lgkmcnt(0)
	s_setprio 1
	s_barrier
	v_mfma_f32_16x16x32_bf16 v[64:67], v[136:139], v[190:193], v[64:67]
	v_mfma_f32_16x16x32_bf16 v[60:63], v[144:147], v[190:193], v[60:63]
	v_mfma_f32_16x16x32_bf16 v[56:59], v[136:139], v[206:209], v[56:59]
	v_mfma_f32_16x16x32_bf16 v[52:55], v[144:147], v[206:209], v[52:55]
	v_mfma_f32_16x16x32_bf16 v[48:51], v[136:139], v[214:217], v[48:51]
	v_mfma_f32_16x16x32_bf16 v[44:47], v[144:147], v[214:217], v[44:47]
	v_mfma_f32_16x16x32_bf16 v[40:43], v[136:139], v[222:225], v[40:43]
	v_mfma_f32_16x16x32_bf16 v[36:39], v[144:147], v[222:225], v[36:39]
	v_mfma_f32_16x16x32_bf16 v[64:67], v[140:143], v[194:197], v[64:67]
	v_mfma_f32_16x16x32_bf16 v[60:63], v[148:151], v[194:197], v[60:63]
	v_mfma_f32_16x16x32_bf16 v[56:59], v[140:143], v[210:213], v[56:59]
	v_mfma_f32_16x16x32_bf16 v[52:55], v[148:151], v[210:213], v[52:55]
	v_mfma_f32_16x16x32_bf16 v[48:51], v[140:143], v[218:221], v[48:51]
	v_mfma_f32_16x16x32_bf16 v[44:47], v[148:151], v[218:221], v[44:47]
	v_mfma_f32_16x16x32_bf16 v[40:43], v[140:143], v[226:229], v[40:43]
	v_mfma_f32_16x16x32_bf16 v[36:39], v[148:151], v[226:229], v[36:39]
	s_setprio 0
	s_setprio 1
	v_mfma_f32_16x16x32_bf16 v[32:35], v[152:155], v[190:193], v[32:35]
	v_mfma_f32_16x16x32_bf16 v[28:31], v[160:163], v[190:193], v[28:31]
	v_mfma_f32_16x16x32_bf16 v[24:27], v[152:155], v[206:209], v[24:27]
	v_mfma_f32_16x16x32_bf16 v[20:23], v[160:163], v[206:209], v[20:23]
	v_mfma_f32_16x16x32_bf16 v[16:19], v[152:155], v[214:217], v[16:19]
	v_mfma_f32_16x16x32_bf16 v[12:15], v[160:163], v[214:217], v[12:15]
	v_mfma_f32_16x16x32_bf16 v[8:11], v[152:155], v[222:225], v[8:11]
	v_mfma_f32_16x16x32_bf16 v[4:7], v[160:163], v[222:225], v[4:7]
	v_mfma_f32_16x16x32_bf16 v[32:35], v[156:159], v[194:197], v[32:35]
	v_mfma_f32_16x16x32_bf16 v[28:31], v[186:189], v[194:197], v[28:31]
	v_mfma_f32_16x16x32_bf16 v[24:27], v[156:159], v[210:213], v[24:27]
	v_mfma_f32_16x16x32_bf16 v[20:23], v[186:189], v[210:213], v[20:23]
	v_mfma_f32_16x16x32_bf16 v[16:19], v[156:159], v[218:221], v[16:19]
	v_mfma_f32_16x16x32_bf16 v[12:15], v[186:189], v[218:221], v[12:15]
	v_mfma_f32_16x16x32_bf16 v[8:11], v[156:159], v[226:229], v[8:11]
	v_mfma_f32_16x16x32_bf16 v[4:7], v[186:189], v[226:229], v[4:7]
	s_setprio 0
	s_barrier
	s_add_i32 s55, 0, 0x18000
	s_add_i32 s78, 0, 0x1c000
	v_add_u32_e32 v148, s55, v204
	v_add_u32_e32 v186, s78, v204
	ds_read_b128 v[136:139], v148
	ds_read_b128 v[140:143], v148 offset:1024
	ds_read_b128 v[144:147], v148 offset:2048
	ds_read_b128 v[148:151], v148 offset:3072
	ds_read_b128 v[152:155], v186
	ds_read_b128 v[156:159], v186 offset:1024
	ds_read_b128 v[160:163], v186 offset:2048
	ds_read_b128 v[186:189], v186 offset:3072
	s_add_u32 s10, s10, 0x80000
	s_addc_u32 s11, s11, 0
	s_mov_b32 m0, s31
	v_lshl_add_u64 v[238:239], s[10:11], 0, v[168:169]
	ds_read_b128 v[190:193], v205 offset:32768
	ds_read_b128 v[194:197], v205 offset:33792
	ds_read_b128 v[206:209], v205 offset:34816
	ds_read_b128 v[210:213], v205 offset:35840
	ds_read_b128 v[214:217], v205 offset:36864
	ds_read_b128 v[218:221], v205 offset:37888
	ds_read_b128 v[222:225], v205 offset:38912
	ds_read_b128 v[226:229], v205 offset:39936
	global_load_lds_dwordx4 v[238:239], off
	v_lshl_add_u64 v[238:239], s[10:11], 0, v[172:173]
	s_mov_b32 m0, s36
	s_nop 0
	global_load_lds_dwordx4 v[238:239], off
	s_waitcnt vmcnt(8)
	s_waitcnt lgkmcnt(0)
	s_setprio 1
	s_barrier
	v_mfma_f32_16x16x32_bf16 v[128:131], v[136:139], v[190:193], v[128:131]
	v_mfma_f32_16x16x32_bf16 v[124:127], v[144:147], v[190:193], v[124:127]
	v_mfma_f32_16x16x32_bf16 v[120:123], v[136:139], v[206:209], v[120:123]
	v_mfma_f32_16x16x32_bf16 v[116:119], v[144:147], v[206:209], v[116:119]
	v_mfma_f32_16x16x32_bf16 v[112:115], v[136:139], v[214:217], v[112:115]
	v_mfma_f32_16x16x32_bf16 v[108:111], v[144:147], v[214:217], v[108:111]
	v_mfma_f32_16x16x32_bf16 v[104:107], v[136:139], v[222:225], v[104:107]
	v_mfma_f32_16x16x32_bf16 v[100:103], v[144:147], v[222:225], v[100:103]
	v_mfma_f32_16x16x32_bf16 v[128:131], v[140:143], v[194:197], v[128:131]
	v_mfma_f32_16x16x32_bf16 v[124:127], v[148:151], v[194:197], v[124:127]
	v_mfma_f32_16x16x32_bf16 v[120:123], v[140:143], v[210:213], v[120:123]
	v_mfma_f32_16x16x32_bf16 v[116:119], v[148:151], v[210:213], v[116:119]
	v_mfma_f32_16x16x32_bf16 v[112:115], v[140:143], v[218:221], v[112:115]
	v_mfma_f32_16x16x32_bf16 v[108:111], v[148:151], v[218:221], v[108:111]
	v_mfma_f32_16x16x32_bf16 v[104:107], v[140:143], v[226:229], v[104:107]
	v_mfma_f32_16x16x32_bf16 v[100:103], v[148:151], v[226:229], v[100:103]
	s_setprio 0
	s_setprio 1
	v_mfma_f32_16x16x32_bf16 v[96:99], v[152:155], v[190:193], v[96:99]
	v_mfma_f32_16x16x32_bf16 v[92:95], v[160:163], v[190:193], v[92:95]
	v_mfma_f32_16x16x32_bf16 v[88:91], v[152:155], v[206:209], v[88:91]
	v_mfma_f32_16x16x32_bf16 v[84:87], v[160:163], v[206:209], v[84:87]
	v_mfma_f32_16x16x32_bf16 v[80:83], v[152:155], v[214:217], v[80:83]
	v_mfma_f32_16x16x32_bf16 v[76:79], v[160:163], v[214:217], v[76:79]
	v_mfma_f32_16x16x32_bf16 v[72:75], v[152:155], v[222:225], v[72:75]
	v_mfma_f32_16x16x32_bf16 v[68:71], v[160:163], v[222:225], v[68:71]
	v_mfma_f32_16x16x32_bf16 v[96:99], v[156:159], v[194:197], v[96:99]
	v_mfma_f32_16x16x32_bf16 v[92:95], v[186:189], v[194:197], v[92:95]
	v_mfma_f32_16x16x32_bf16 v[88:91], v[156:159], v[210:213], v[88:91]
	v_mfma_f32_16x16x32_bf16 v[84:87], v[186:189], v[210:213], v[84:87]
	v_mfma_f32_16x16x32_bf16 v[80:83], v[156:159], v[218:221], v[80:83]
	v_mfma_f32_16x16x32_bf16 v[76:79], v[186:189], v[218:221], v[76:79]
	v_mfma_f32_16x16x32_bf16 v[72:75], v[156:159], v[226:229], v[72:75]
	v_mfma_f32_16x16x32_bf16 v[68:71], v[186:189], v[226:229], v[68:71]
	s_setprio 0
	s_barrier
	s_add_i32 s10, s55, s24
	v_lshl_add_u64 v[230:231], v[230:231], 0, s[28:29]
	s_mov_b32 m0, s10
	ds_read_b128 v[190:193], v205 offset:49152
	ds_read_b128 v[194:197], v205 offset:50176
	ds_read_b128 v[206:209], v205 offset:51200
	ds_read_b128 v[210:213], v205 offset:52224
	ds_read_b128 v[214:217], v205 offset:53248
	ds_read_b128 v[218:221], v205 offset:54272
	ds_read_b128 v[222:225], v205 offset:55296
	ds_read_b128 v[226:229], v205 offset:56320
	global_load_lds_dwordx4 v[230:231], off
	s_add_i32 m0, s10, 0x2000
	s_add_u32 s8, s8, 0x80080
	v_lshl_add_u64 v[230:231], v[232:233], 0, s[28:29]
	s_addc_u32 s9, s9, 0
	s_add_i32 s10, s78, s24
	global_load_lds_dwordx4 v[230:231], off
	v_lshl_add_u64 v[230:231], s[8:9], 0, v[170:171]
	s_mov_b32 m0, s10
	s_nop 0
	global_load_lds_dwordx4 v[230:231], off
	v_lshl_add_u64 v[230:231], s[8:9], 0, v[174:175]
	s_add_i32 m0, s10, 0x2000
	s_nop 0
	global_load_lds_dwordx4 v[230:231], off
	v_lshl_add_u64 v[230:231], v[234:235], 0, s[28:29]
	s_mov_b32 m0, s45
	s_nop 0
	global_load_lds_dwordx4 v[230:231], off
	v_lshl_add_u64 v[230:231], v[236:237], 0, s[28:29]
	s_mov_b32 m0, s60
	s_nop 0
	global_load_lds_dwordx4 v[230:231], off
	s_waitcnt vmcnt(8)
	s_waitcnt lgkmcnt(0)
	s_setprio 1
	s_barrier
	v_mfma_f32_16x16x32_bf16 v[64:67], v[136:139], v[190:193], v[64:67]
	v_mfma_f32_16x16x32_bf16 v[60:63], v[144:147], v[190:193], v[60:63]
	v_mfma_f32_16x16x32_bf16 v[56:59], v[136:139], v[206:209], v[56:59]
	v_mfma_f32_16x16x32_bf16 v[52:55], v[144:147], v[206:209], v[52:55]
	v_mfma_f32_16x16x32_bf16 v[48:51], v[136:139], v[214:217], v[48:51]
	v_mfma_f32_16x16x32_bf16 v[44:47], v[144:147], v[214:217], v[44:47]
	v_mfma_f32_16x16x32_bf16 v[40:43], v[136:139], v[222:225], v[40:43]
	v_mfma_f32_16x16x32_bf16 v[36:39], v[144:147], v[222:225], v[36:39]
	v_mfma_f32_16x16x32_bf16 v[64:67], v[140:143], v[194:197], v[64:67]
	v_mfma_f32_16x16x32_bf16 v[60:63], v[148:151], v[194:197], v[60:63]
	v_mfma_f32_16x16x32_bf16 v[56:59], v[140:143], v[210:213], v[56:59]
	v_mfma_f32_16x16x32_bf16 v[52:55], v[148:151], v[210:213], v[52:55]
	v_mfma_f32_16x16x32_bf16 v[48:51], v[140:143], v[218:221], v[48:51]
	v_mfma_f32_16x16x32_bf16 v[44:47], v[148:151], v[218:221], v[44:47]
	v_mfma_f32_16x16x32_bf16 v[40:43], v[140:143], v[226:229], v[40:43]
	v_mfma_f32_16x16x32_bf16 v[36:39], v[148:151], v[226:229], v[36:39]
	s_setprio 0
	s_setprio 1
	v_mfma_f32_16x16x32_bf16 v[32:35], v[152:155], v[190:193], v[32:35]
	v_mfma_f32_16x16x32_bf16 v[28:31], v[160:163], v[190:193], v[28:31]
	v_mfma_f32_16x16x32_bf16 v[24:27], v[152:155], v[206:209], v[24:27]
	v_mfma_f32_16x16x32_bf16 v[20:23], v[160:163], v[206:209], v[20:23]
	v_mfma_f32_16x16x32_bf16 v[16:19], v[152:155], v[214:217], v[16:19]
	v_mfma_f32_16x16x32_bf16 v[12:15], v[160:163], v[214:217], v[12:15]
	v_mfma_f32_16x16x32_bf16 v[8:11], v[152:155], v[222:225], v[8:11]
	v_mfma_f32_16x16x32_bf16 v[4:7], v[160:163], v[222:225], v[4:7]
	v_mfma_f32_16x16x32_bf16 v[32:35], v[156:159], v[194:197], v[32:35]
	v_mfma_f32_16x16x32_bf16 v[28:31], v[186:189], v[194:197], v[28:31]
	v_mfma_f32_16x16x32_bf16 v[24:27], v[156:159], v[210:213], v[24:27]
	v_mfma_f32_16x16x32_bf16 v[20:23], v[186:189], v[210:213], v[20:23]
	v_mfma_f32_16x16x32_bf16 v[16:19], v[156:159], v[218:221], v[16:19]
	v_mfma_f32_16x16x32_bf16 v[12:15], v[186:189], v[218:221], v[12:15]
	v_mfma_f32_16x16x32_bf16 v[8:11], v[156:159], v[226:229], v[8:11]
	v_mfma_f32_16x16x32_bf16 v[4:7], v[186:189], v[226:229], v[4:7]
	s_setprio 0
	s_barrier
	s_add_i32 s43, s43, 2
	s_add_u32 s0, s0, 0x100
	s_addc_u32 s1, s1, 0
	s_cmp_gt_u32 s43, 29
	s_cbranch_scc0 .LBB0_623
	s_and_b64 vcc, exec, s[50:51]
	s_cbranch_vccz .LBB0_626
	s_barrier

.LBB0_866:
	s_add_u32 s24, s34, s10
	s_addc_u32 s25, s35, s11
	s_add_u32 s24, s24, 0x100
	s_addc_u32 s25, s25, 0
	s_add_u32 s67, s60, s10
	s_addc_u32 s74, s61, s11
	s_add_i32 s75, 0, 0x10000
	s_cmpk_eq_i32 s10, 0xf00
	s_cselect_b32 s31, s27, s25
	s_cselect_b32 s30, s62, s24
	s_cselect_b32 s25, s15, s74
	s_cselect_b32 s24, s63, s67
	s_add_i32 s67, 0, 0x14000
	v_add_u32_e32 v148, s75, v189
	v_add_u32_e32 v178, s67, v189
	ds_read_b128 v[136:139], v148
	ds_read_b128 v[140:143], v148 offset:1024
	ds_read_b128 v[144:147], v148 offset:2048
	ds_read_b128 v[148:151], v148 offset:3072
	ds_read_b128 v[152:155], v178
	ds_read_b128 v[170:173], v178 offset:1024
	ds_read_b128 v[174:177], v178 offset:2048
	ds_read_b128 v[178:181], v178 offset:3072
	v_lshl_add_u64 v[186:187], v[132:133], 0, s[10:11]
	s_add_i32 m0, s48, 0xc000
	ds_read_b128 v[182:185], v191
	ds_read_b128 v[192:195], v191 offset:1024
	ds_read_b128 v[204:207], v191 offset:2048
	ds_read_b128 v[208:211], v191 offset:3072
	ds_read_b128 v[212:215], v191 offset:4096
	ds_read_b128 v[216:219], v191 offset:5120
	ds_read_b128 v[220:223], v191 offset:6144
	ds_read_b128 v[224:227], v191 offset:7168
	global_load_lds_dwordx4 v[186:187], off
	v_lshl_add_u64 v[186:187], v[134:135], 0, s[10:11]
	s_add_i32 m0, s48, 0xe000
	s_nop 0
	global_load_lds_dwordx4 v[186:187], off
	s_waitcnt vmcnt(8)
	s_waitcnt lgkmcnt(0)
	s_setprio 1
	s_barrier
	v_mfma_f32_16x16x32_bf16 v[128:131], v[136:139], v[182:185], v[128:131]
	v_mfma_f32_16x16x32_bf16 v[124:127], v[144:147], v[182:185], v[124:127]
	v_mfma_f32_16x16x32_bf16 v[120:123], v[136:139], v[204:207], v[120:123]
	v_mfma_f32_16x16x32_bf16 v[116:119], v[144:147], v[204:207], v[116:119]
	v_mfma_f32_16x16x32_bf16 v[112:115], v[136:139], v[212:215], v[112:115]
	v_mfma_f32_16x16x32_bf16 v[108:111], v[144:147], v[212:215], v[108:111]
	v_mfma_f32_16x16x32_bf16 v[104:107], v[136:139], v[220:223], v[104:107]
	v_mfma_f32_16x16x32_bf16 v[100:103], v[144:147], v[220:223], v[100:103]
	v_mfma_f32_16x16x32_bf16 v[128:131], v[140:143], v[192:195], v[128:131]
	v_mfma_f32_16x16x32_bf16 v[124:127], v[148:151], v[192:195], v[124:127]
	v_mfma_f32_16x16x32_bf16 v[120:123], v[140:143], v[208:211], v[120:123]
	v_mfma_f32_16x16x32_bf16 v[116:119], v[148:151], v[208:211], v[116:119]
	v_mfma_f32_16x16x32_bf16 v[112:115], v[140:143], v[216:219], v[112:115]
	v_mfma_f32_16x16x32_bf16 v[108:111], v[148:151], v[216:219], v[108:111]
	v_mfma_f32_16x16x32_bf16 v[104:107], v[140:143], v[224:227], v[104:107]
	v_mfma_f32_16x16x32_bf16 v[100:103], v[148:151], v[224:227], v[100:103]
	s_setprio 0
	s_setprio 1
	v_mfma_f32_16x16x32_bf16 v[96:99], v[152:155], v[182:185], v[96:99]
	v_mfma_f32_16x16x32_bf16 v[92:95], v[174:177], v[182:185], v[92:95]
	v_mfma_f32_16x16x32_bf16 v[88:91], v[152:155], v[204:207], v[88:91]
	v_mfma_f32_16x16x32_bf16 v[84:87], v[174:177], v[204:207], v[84:87]
	v_mfma_f32_16x16x32_bf16 v[80:83], v[152:155], v[212:215], v[80:83]
	v_mfma_f32_16x16x32_bf16 v[76:79], v[174:177], v[212:215], v[76:79]
	v_mfma_f32_16x16x32_bf16 v[72:75], v[152:155], v[220:223], v[72:75]
	v_mfma_f32_16x16x32_bf16 v[68:71], v[174:177], v[220:223], v[68:71]
	v_mfma_f32_16x16x32_bf16 v[96:99], v[170:173], v[192:195], v[96:99]
	v_mfma_f32_16x16x32_bf16 v[92:95], v[178:181], v[192:195], v[92:95]
	v_mfma_f32_16x16x32_bf16 v[88:91], v[170:173], v[208:211], v[88:91]
	v_mfma_f32_16x16x32_bf16 v[84:87], v[178:181], v[208:211], v[84:87]
	v_mfma_f32_16x16x32_bf16 v[80:83], v[170:173], v[216:219], v[80:83]
	v_mfma_f32_16x16x32_bf16 v[76:79], v[178:181], v[216:219], v[76:79]
	v_mfma_f32_16x16x32_bf16 v[72:75], v[170:173], v[224:227], v[72:75]
	v_mfma_f32_16x16x32_bf16 v[68:71], v[178:181], v[224:227], v[68:71]
	s_setprio 0
	s_barrier
	s_add_i32 s74, s75, s47
	v_lshl_add_u64 v[186:187], s[24:25], 0, v[2:3]
	s_mov_b32 m0, s74
	ds_read_b128 v[182:185], v191 offset:16384
	ds_read_b128 v[192:195], v191 offset:17408
	ds_read_b128 v[204:207], v191 offset:18432
	ds_read_b128 v[208:211], v191 offset:19456
	ds_read_b128 v[212:215], v191 offset:20480
	ds_read_b128 v[216:219], v191 offset:21504
	ds_read_b128 v[220:223], v191 offset:22528
	ds_read_b128 v[224:227], v191 offset:23552
	global_load_lds_dwordx4 v[186:187], off
	s_add_i32 m0, s74, 0x2000
	s_add_u32 s74, s24, 0x80000
	v_lshl_add_u64 v[196:197], s[24:25], 0, v[156:157]
	s_addc_u32 s75, s25, 0
	s_add_i32 s67, s67, s47
	global_load_lds_dwordx4 v[196:197], off
	v_lshl_add_u64 v[228:229], s[74:75], 0, v[2:3]
	s_mov_b32 m0, s67
	v_lshl_add_u64 v[230:231], s[30:31], 0, v[158:159]
	global_load_lds_dwordx4 v[228:229], off
	v_lshl_add_u64 v[228:229], s[74:75], 0, v[156:157]
	s_add_i32 m0, s67, 0x2000
	s_nop 0
	global_load_lds_dwordx4 v[228:229], off
	v_lshl_add_u64 v[228:229], s[30:31], 0, v[160:161]
	s_mov_b32 m0, s48
	s_nop 0
	global_load_lds_dwordx4 v[228:229], off
	s_mov_b32 m0, s49
	s_nop 0
	global_load_lds_dwordx4 v[230:231], off
	s_waitcnt vmcnt(8)
	s_waitcnt lgkmcnt(0)
	s_setprio 1
	s_barrier
	v_mfma_f32_16x16x32_bf16 v[64:67], v[136:139], v[182:185], v[64:67]
	v_mfma_f32_16x16x32_bf16 v[60:63], v[144:147], v[182:185], v[60:63]
	v_mfma_f32_16x16x32_bf16 v[56:59], v[136:139], v[204:207], v[56:59]
	v_mfma_f32_16x16x32_bf16 v[52:55], v[144:147], v[204:207], v[52:55]
	v_mfma_f32_16x16x32_bf16 v[48:51], v[136:139], v[212:215], v[48:51]
	v_mfma_f32_16x16x32_bf16 v[44:47], v[144:147], v[212:215], v[44:47]
	v_mfma_f32_16x16x32_bf16 v[40:43], v[136:139], v[220:223], v[40:43]
	v_mfma_f32_16x16x32_bf16 v[36:39], v[144:147], v[220:223], v[36:39]
	v_mfma_f32_16x16x32_bf16 v[64:67], v[140:143], v[192:195], v[64:67]
	v_mfma_f32_16x16x32_bf16 v[60:63], v[148:151], v[192:195], v[60:63]
	v_mfma_f32_16x16x32_bf16 v[56:59], v[140:143], v[208:211], v[56:59]
	v_mfma_f32_16x16x32_bf16 v[52:55], v[148:151], v[208:211], v[52:55]
	v_mfma_f32_16x16x32_bf16 v[48:51], v[140:143], v[216:219], v[48:51]
	v_mfma_f32_16x16x32_bf16 v[44:47], v[148:151], v[216:219], v[44:47]
	v_mfma_f32_16x16x32_bf16 v[40:43], v[140:143], v[224:227], v[40:43]
	v_mfma_f32_16x16x32_bf16 v[36:39], v[148:151], v[224:227], v[36:39]
	s_setprio 0
	s_setprio 1
	v_mfma_f32_16x16x32_bf16 v[32:35], v[152:155], v[182:185], v[32:35]
	v_mfma_f32_16x16x32_bf16 v[28:31], v[174:177], v[182:185], v[28:31]
	v_mfma_f32_16x16x32_bf16 v[24:27], v[152:155], v[204:207], v[24:27]
	v_mfma_f32_16x16x32_bf16 v[20:23], v[174:177], v[204:207], v[20:23]
	v_mfma_f32_16x16x32_bf16 v[16:19], v[152:155], v[212:215], v[16:19]
	v_mfma_f32_16x16x32_bf16 v[12:15], v[174:177], v[212:215], v[12:15]
	v_mfma_f32_16x16x32_bf16 v[8:11], v[152:155], v[220:223], v[8:11]
	v_mfma_f32_16x16x32_bf16 v[4:7], v[174:177], v[220:223], v[4:7]
	v_mfma_f32_16x16x32_bf16 v[32:35], v[170:173], v[192:195], v[32:35]
	v_mfma_f32_16x16x32_bf16 v[28:31], v[178:181], v[192:195], v[28:31]
	v_mfma_f32_16x16x32_bf16 v[24:27], v[170:173], v[208:211], v[24:27]
	v_mfma_f32_16x16x32_bf16 v[20:23], v[178:181], v[208:211], v[20:23]
	v_mfma_f32_16x16x32_bf16 v[16:19], v[170:173], v[216:219], v[16:19]
	v_mfma_f32_16x16x32_bf16 v[12:15], v[178:181], v[216:219], v[12:15]
	v_mfma_f32_16x16x32_bf16 v[8:11], v[170:173], v[224:227], v[8:11]
	v_mfma_f32_16x16x32_bf16 v[4:7], v[178:181], v[224:227], v[4:7]
	s_setprio 0
	s_barrier
	s_add_i32 s67, 0, 0x18000
	s_add_i32 s74, 0, 0x1c000
	v_add_u32_e32 v148, s67, v189
	v_add_u32_e32 v178, s74, v189
	ds_read_b128 v[136:139], v148
	ds_read_b128 v[140:143], v148 offset:1024
	ds_read_b128 v[144:147], v148 offset:2048
	ds_read_b128 v[148:151], v148 offset:3072
	ds_read_b128 v[152:155], v178
	ds_read_b128 v[170:173], v178 offset:1024
	ds_read_b128 v[174:177], v178 offset:2048
	ds_read_b128 v[178:181], v178 offset:3072
	s_add_u32 s30, s30, 0x80000
	s_addc_u32 s31, s31, 0
	s_mov_b32 m0, s50
	v_lshl_add_u64 v[232:233], s[30:31], 0, v[160:161]
	ds_read_b128 v[182:185], v191 offset:32768
	ds_read_b128 v[192:195], v191 offset:33792
	ds_read_b128 v[204:207], v191 offset:34816
	ds_read_b128 v[208:211], v191 offset:35840
	ds_read_b128 v[212:215], v191 offset:36864
	ds_read_b128 v[216:219], v191 offset:37888
	ds_read_b128 v[220:223], v191 offset:38912
	ds_read_b128 v[224:227], v191 offset:39936
	global_load_lds_dwordx4 v[232:233], off
	v_lshl_add_u64 v[232:233], s[30:31], 0, v[158:159]
	s_mov_b32 m0, s51
	s_nop 0
	global_load_lds_dwordx4 v[232:233], off
	s_waitcnt vmcnt(8)
	s_waitcnt lgkmcnt(0)
	s_setprio 1
	s_barrier
	v_mfma_f32_16x16x32_bf16 v[128:131], v[136:139], v[182:185], v[128:131]
	v_mfma_f32_16x16x32_bf16 v[124:127], v[144:147], v[182:185], v[124:127]
	v_mfma_f32_16x16x32_bf16 v[120:123], v[136:139], v[204:207], v[120:123]
	v_mfma_f32_16x16x32_bf16 v[116:119], v[144:147], v[204:207], v[116:119]
	v_mfma_f32_16x16x32_bf16 v[112:115], v[136:139], v[212:215], v[112:115]
	v_mfma_f32_16x16x32_bf16 v[108:111], v[144:147], v[212:215], v[108:111]
	v_mfma_f32_16x16x32_bf16 v[104:107], v[136:139], v[220:223], v[104:107]
	v_mfma_f32_16x16x32_bf16 v[100:103], v[144:147], v[220:223], v[100:103]
	v_mfma_f32_16x16x32_bf16 v[128:131], v[140:143], v[192:195], v[128:131]
	v_mfma_f32_16x16x32_bf16 v[124:127], v[148:151], v[192:195], v[124:127]
	v_mfma_f32_16x16x32_bf16 v[120:123], v[140:143], v[208:211], v[120:123]
	v_mfma_f32_16x16x32_bf16 v[116:119], v[148:151], v[208:211], v[116:119]
	v_mfma_f32_16x16x32_bf16 v[112:115], v[140:143], v[216:219], v[112:115]
	v_mfma_f32_16x16x32_bf16 v[108:111], v[148:151], v[216:219], v[108:111]
	v_mfma_f32_16x16x32_bf16 v[104:107], v[140:143], v[224:227], v[104:107]
	v_mfma_f32_16x16x32_bf16 v[100:103], v[148:151], v[224:227], v[100:103]
	s_setprio 0
	s_setprio 1
	v_mfma_f32_16x16x32_bf16 v[96:99], v[152:155], v[182:185], v[96:99]
	v_mfma_f32_16x16x32_bf16 v[92:95], v[174:177], v[182:185], v[92:95]
	v_mfma_f32_16x16x32_bf16 v[88:91], v[152:155], v[204:207], v[88:91]
	v_mfma_f32_16x16x32_bf16 v[84:87], v[174:177], v[204:207], v[84:87]
	v_mfma_f32_16x16x32_bf16 v[80:83], v[152:155], v[212:215], v[80:83]
	v_mfma_f32_16x16x32_bf16 v[76:79], v[174:177], v[212:215], v[76:79]
	v_mfma_f32_16x16x32_bf16 v[72:75], v[152:155], v[220:223], v[72:75]
	v_mfma_f32_16x16x32_bf16 v[68:71], v[174:177], v[220:223], v[68:71]
	v_mfma_f32_16x16x32_bf16 v[96:99], v[170:173], v[192:195], v[96:99]
	v_mfma_f32_16x16x32_bf16 v[92:95], v[178:181], v[192:195], v[92:95]
	v_mfma_f32_16x16x32_bf16 v[88:91], v[170:173], v[208:211], v[88:91]
	v_mfma_f32_16x16x32_bf16 v[84:87], v[178:181], v[208:211], v[84:87]
	v_mfma_f32_16x16x32_bf16 v[80:83], v[170:173], v[216:219], v[80:83]
	v_mfma_f32_16x16x32_bf16 v[76:79], v[178:181], v[216:219], v[76:79]
	v_mfma_f32_16x16x32_bf16 v[72:75], v[170:173], v[224:227], v[72:75]
	v_mfma_f32_16x16x32_bf16 v[68:71], v[178:181], v[224:227], v[68:71]
	s_setprio 0
	s_barrier
	s_add_i32 s30, s67, s47
	v_lshl_add_u64 v[186:187], v[186:187], 0, s[28:29]
	s_mov_b32 m0, s30
	ds_read_b128 v[182:185], v191 offset:49152
	ds_read_b128 v[192:195], v191 offset:50176
	ds_read_b128 v[204:207], v191 offset:51200
	ds_read_b128 v[208:211], v191 offset:52224
	ds_read_b128 v[212:215], v191 offset:53248
	ds_read_b128 v[216:219], v191 offset:54272
	ds_read_b128 v[220:223], v191 offset:55296
	ds_read_b128 v[224:227], v191 offset:56320
	global_load_lds_dwordx4 v[186:187], off
	s_add_i32 m0, s30, 0x2000
	s_add_u32 s24, s24, 0x80080
	v_lshl_add_u64 v[186:187], v[196:197], 0, s[28:29]
	s_addc_u32 s25, s25, 0
	s_add_i32 s30, s74, s47
	global_load_lds_dwordx4 v[186:187], off
	v_lshl_add_u64 v[186:187], s[24:25], 0, v[2:3]
	s_mov_b32 m0, s30
	s_nop 0
	global_load_lds_dwordx4 v[186:187], off
	v_lshl_add_u64 v[186:187], s[24:25], 0, v[156:157]
	s_add_i32 m0, s30, 0x2000
	s_nop 0
	global_load_lds_dwordx4 v[186:187], off
	v_lshl_add_u64 v[186:187], v[228:229], 0, s[28:29]
	s_mov_b32 m0, s52
	s_nop 0
	global_load_lds_dwordx4 v[186:187], off
	v_lshl_add_u64 v[186:187], v[230:231], 0, s[28:29]
	s_mov_b32 m0, s53
	s_nop 0
	global_load_lds_dwordx4 v[186:187], off
	s_waitcnt vmcnt(8)
	s_waitcnt lgkmcnt(0)
	s_setprio 1
	s_barrier
	v_mfma_f32_16x16x32_bf16 v[64:67], v[136:139], v[182:185], v[64:67]
	v_mfma_f32_16x16x32_bf16 v[60:63], v[144:147], v[182:185], v[60:63]
	v_mfma_f32_16x16x32_bf16 v[56:59], v[136:139], v[204:207], v[56:59]
	v_mfma_f32_16x16x32_bf16 v[52:55], v[144:147], v[204:207], v[52:55]
	v_mfma_f32_16x16x32_bf16 v[48:51], v[136:139], v[212:215], v[48:51]
	v_mfma_f32_16x16x32_bf16 v[44:47], v[144:147], v[212:215], v[44:47]
	v_mfma_f32_16x16x32_bf16 v[40:43], v[136:139], v[220:223], v[40:43]
	v_mfma_f32_16x16x32_bf16 v[36:39], v[144:147], v[220:223], v[36:39]
	v_mfma_f32_16x16x32_bf16 v[64:67], v[140:143], v[192:195], v[64:67]
	v_mfma_f32_16x16x32_bf16 v[60:63], v[148:151], v[192:195], v[60:63]
	v_mfma_f32_16x16x32_bf16 v[56:59], v[140:143], v[208:211], v[56:59]
	v_mfma_f32_16x16x32_bf16 v[52:55], v[148:151], v[208:211], v[52:55]
	v_mfma_f32_16x16x32_bf16 v[48:51], v[140:143], v[216:219], v[48:51]
	v_mfma_f32_16x16x32_bf16 v[44:47], v[148:151], v[216:219], v[44:47]
	v_mfma_f32_16x16x32_bf16 v[40:43], v[140:143], v[224:227], v[40:43]
	v_mfma_f32_16x16x32_bf16 v[36:39], v[148:151], v[224:227], v[36:39]
	s_setprio 0
	s_setprio 1
	v_mfma_f32_16x16x32_bf16 v[32:35], v[152:155], v[182:185], v[32:35]
	v_mfma_f32_16x16x32_bf16 v[28:31], v[174:177], v[182:185], v[28:31]
	v_mfma_f32_16x16x32_bf16 v[24:27], v[152:155], v[204:207], v[24:27]
	v_mfma_f32_16x16x32_bf16 v[20:23], v[174:177], v[204:207], v[20:23]
	v_mfma_f32_16x16x32_bf16 v[16:19], v[152:155], v[212:215], v[16:19]
	v_mfma_f32_16x16x32_bf16 v[12:15], v[174:177], v[212:215], v[12:15]
	v_mfma_f32_16x16x32_bf16 v[8:11], v[152:155], v[220:223], v[8:11]
	v_mfma_f32_16x16x32_bf16 v[4:7], v[174:177], v[220:223], v[4:7]
	v_mfma_f32_16x16x32_bf16 v[32:35], v[170:173], v[192:195], v[32:35]
	v_mfma_f32_16x16x32_bf16 v[28:31], v[178:181], v[192:195], v[28:31]
	v_mfma_f32_16x16x32_bf16 v[24:27], v[170:173], v[208:211], v[24:27]
	v_mfma_f32_16x16x32_bf16 v[20:23], v[178:181], v[208:211], v[20:23]
	v_mfma_f32_16x16x32_bf16 v[16:19], v[170:173], v[216:219], v[16:19]
	v_mfma_f32_16x16x32_bf16 v[12:15], v[178:181], v[216:219], v[12:15]
	v_mfma_f32_16x16x32_bf16 v[8:11], v[170:173], v[224:227], v[8:11]
	v_mfma_f32_16x16x32_bf16 v[4:7], v[178:181], v[224:227], v[4:7]
	s_setprio 0
	s_barrier
	s_add_i32 s66, s66, 2
	s_add_u32 s10, s10, 0x100
	s_addc_u32 s11, s11, 0
	s_cmp_gt_u32 s66, 29
	s_cbranch_scc0 .LBB0_866
	s_and_b64 vcc, exec, s[12:13]
	s_cbranch_vccz .LBB0_869
	s_barrier
